# gate/up GEMM: each workgroup computes a pair of adjacent 128x128 tiles sharing the A tile (LDS-DMA bytes per flop x0.75; 80 KB LDS, +4 KB static)
# speedup vs baseline: 1.0350x; 1.0350x over previous
.LBB0_71:
	v_readlane_b32 s0, v255, 0
	s_cmp_lt_i32 s0, 4
	s_cbranch_scc1 .LBB0_92
	s_cmp_gt_i32 s0, 6
	s_cbranch_scc0 .LBB0_93
	s_cmp_gt_i32 s0, 7
	s_mov_b64 s[0:1], -1
	s_cbranch_scc0 .LBB0_79
	v_readlane_b32 s0, v255, 0
	s_cmp_eq_u32 s0, 8
	s_cbranch_scc0 .LBB0_78
	v_mov_b32_e32 v2, v0
	s_mov_b32 s0, s2
	s_cmpk_gt_i32 s0, 0x57f
	s_cbranch_scc1 .LBB0_78
	v_readlane_b32 s6, v254, 62
	v_ashrrev_i32_e32 v4, 6, v2
	v_readlane_b32 s7, v254, 63
	s_add_u32 s1, s6, 0xc98000
	s_addc_u32 s4, s7, 0
	v_lshlrev_b32_e32 v7, 2, v4
	v_bfe_u32 v3, v2, 3, 3
	s_add_u32 s5, s6, 0x718000
	v_bfe_u32 v5, v2, 1, 3
	v_bfe_u32 v6, v2, 5, 1
	v_and_b32_e32 v7, 4, v7
	v_bfe_u32 v8, v2, 4, 2
	v_and_b32_e32 v9, 7, v2
	v_lshl_or_b32 v86, v4, 3, v3
	s_addc_u32 s6, s7, 0
	v_lshrrev_b32_e32 v3, 1, v2
	v_bitop3_b32 v7, v7, v9, v8 bitop3:0x36
	v_bitop3_b32 v10, v6, v5, 6 bitop3:0x36
	v_ashrrev_i32_e32 v8, 7, v2
	v_and_b32_e32 v2, 31, v2
	v_lshlrev_b32_e32 v130, 4, v7
	v_lshlrev_b32_e32 v7, 5, v4
	v_lshlrev_b32_e32 v9, 2, v6
	v_lshl_add_u32 v87, v10, 4, 0
	v_bitop3_b32 v10, v6, v3, 7 bitop3:0x78
	v_bitop3_b32 v13, v6, v5, 2 bitop3:0x36
	v_bitop3_b32 v5, v6, v5, 4 bitop3:0x36
	v_mov_b32_e32 v6, s4
	v_mov_b32_e32 v14, s6
	v_cmp_gt_i32_e64 s[36:37], 64, v86
	v_mov_b32_e32 v15, s1
	v_mov_b32_e32 v16, s5
	v_and_or_b32 v88, v7, 32, v2
	v_lshlrev_b32_e32 v12, 7, v2
	v_cndmask_b32_e64 v3, v6, v14, s[36:37]
	v_cndmask_b32_e64 v2, v15, v16, s[36:37]
	v_cmp_gt_i32_e64 s[38:39], 32, v86
	v_lshl_add_u64 v[68:69], v[2:3], 0, v[130:131]
	v_cmp_gt_i32_e32 vcc, 0, v4
	v_cndmask_b32_e64 v3, v6, v14, s[38:39]
	v_cndmask_b32_e64 v2, v15, v16, s[38:39]
	s_movk_i32 s1, 0xffe0
	v_lshl_add_u64 v[70:71], v[2:3], 0, v[130:131]
	v_cndmask_b32_e32 v3, v6, v14, vcc
	v_cndmask_b32_e32 v2, v15, v16, vcc
	v_cmp_gt_i32_e64 s[40:41], s1, v86
	v_readlane_b32 s10, v253, 14
	v_lshlrev_b32_e32 v11, 13, v8
	v_lshl_add_u64 v[72:73], v[2:3], 0, v[130:131]
	v_cndmask_b32_e64 v3, v6, v14, s[40:41]
	v_cndmask_b32_e64 v2, v15, v16, s[40:41]
	v_lshl_add_u32 v94, v5, 4, 0
	v_lshl_add_u32 v95, v13, 4, 0
	v_lshl_add_u32 v96, v10, 4, 0
	v_readlane_b32 s11, v253, 15
	v_add_u32_e32 v7, 64, v86
	v_lshl_add_u32 v92, v4, 10, 0
	v_lshl_add_u64 v[74:75], v[2:3], 0, v[130:131]
	v_add_u32_e32 v2, v87, v11
	v_add_u32_e32 v3, v94, v11
	v_add_u32_e32 v4, v95, v11
	v_add_u32_e32 v5, v96, v11
	v_readlane_b32 s48, v252, 2
	v_lshl_add_u64 v[66:67], s[10:11], 0, v[130:131]
	v_lshlrev_b32_e32 v89, 7, v88
	v_add_u32_e32 v90, 32, v86
	v_add_u32_e32 v91, 0x60, v86
	v_cndmask_b32_e32 v93, v86, v7, vcc
	v_lshl_or_b32 v97, v8, 6, v9
	v_add_u32_e32 v98, v5, v12
	v_add_u32_e32 v99, v4, v12
	v_add_u32_e32 v100, v3, v12
	v_add_u32_e32 v101, v2, v12
	v_readlane_b32 s49, v252, 3
	s_movk_i32 s50, 0x1600
	s_mov_b64 s[96:97], 0x10000
	s_mov_b64 s[52:53], 0x10700
	s_mov_b64 s[54:55], 0x20700
	s_mov_b64 s[56:57], 0x30700
	s_mov_b64 s[58:59], 0x10780
	s_mov_b64 s[64:65], 0x20780
	s_mov_b64 s[66:67], 0x30780
	s_mov_b64 s[20:21], 0x480
	s_mov_b64 s[28:29], 0x500
	s_mov_b64 s[30:31], 0x580
	s_mov_b64 s[34:35], 0x600
	s_mov_b64 s[88:89], 0x680
	s_mov_b64 s[94:95], 0x700
	v_writelane_b32 v255, s0, 47
	s_mov_b32 s4, 0
	s_nop 0
	v_writelane_b32 v255, s4, 48
	v_mov_b32_e32 v196, 0x12ff0
	ds_read_b32 v205, v196 offset:4
	ds_read_b32 v196, v196
	s_waitcnt lgkmcnt(0)
	s_lshr_b32 s1, s0, 6
	s_lshl_b32 s1, s1, 7
	s_and_b32 s0, s0, 63
	s_or_b32 s0, s0, s1
.LBB0_77:
	s_and_b32 s4, s0, 0xffffffc0
	s_sub_i32 s5, s4, 64
	v_mov_b32_e32 v6, s5
	v_mov_b32_e32 v7, s4
	v_cndmask_b32_e64 v4, v6, v7, s[36:37]
	v_add_u32_e32 v4, v4, v86
	v_ashrrev_i32_e32 v5, 31, v4
	v_lshlrev_b64 v[4:5], 11, v[4:5]
	s_lshl_b32 s1, s0, 7
	v_lshl_add_u64 v[84:85], v[68:69], 0, v[4:5]
	v_cndmask_b32_e64 v4, v6, v7, s[38:39]
	s_and_b32 s1, s1, 0x1f80
	v_add_u32_e32 v4, v90, v4
	v_add_u32_e32 v2, s1, v86
	v_ashrrev_i32_e32 v5, 31, v4
	v_ashrrev_i32_e32 v3, 31, v2
	v_lshlrev_b64 v[4:5], 11, v[4:5]
	v_lshlrev_b64 v[2:3], 11, v[2:3]
	v_lshl_add_u64 v[82:83], v[70:71], 0, v[4:5]
	v_add_u32_e32 v4, s4, v93
	v_readfirstlane_b32 s27, v92
	v_add_u32_e32 v114, 0x8000, v92
	v_ashrrev_i32_e32 v5, 31, v4
	v_lshl_add_u64 v[78:79], v[66:67], 0, v[2:3]
	s_mov_b32 m0, s27
	v_readfirstlane_b32 s44, v114
	v_add_u32_e32 v115, 0x1000, v92
	v_lshlrev_b64 v[4:5], 11, v[4:5]
	global_load_lds_dwordx4 v[78:79], off
	s_mov_b32 m0, s44
	v_readfirstlane_b32 s45, v115
	v_add_u32_e32 v116, 0x9000, v92
	v_lshl_add_u64 v[80:81], v[72:73], 0, v[4:5]
	v_cndmask_b32_e64 v4, v6, v7, s[40:41]
	global_load_lds_dwordx4 v[84:85], off
	v_lshl_add_u64 v[2:3], v[78:79], 0, s[96:97]
	s_mov_b32 m0, s45
	v_readfirstlane_b32 s46, v116
	v_add_u32_e32 v117, 0x2000, v92
	v_add_u32_e32 v4, v91, v4
	global_load_lds_dwordx4 v[2:3], off
	s_mov_b32 m0, s46
	s_mov_b64 s[6:7], 0x20000
	v_readfirstlane_b32 s47, v117
	v_add_u32_e32 v113, 0xa000, v92
	v_ashrrev_i32_e32 v5, 31, v4
	global_load_lds_dwordx4 v[82:83], off
	v_lshl_add_u64 v[2:3], v[78:79], 0, s[6:7]
	s_mov_b32 m0, s47
	v_readfirstlane_b32 s43, v113
	v_add_u32_e32 v112, 0x3000, v92
	v_lshlrev_b64 v[4:5], 11, v[4:5]
	global_load_lds_dwordx4 v[2:3], off
	s_mov_b32 m0, s43
	s_mov_b64 s[6:7], 0x30000
	v_readfirstlane_b32 s42, v112
	v_add_u32_e32 v109, 0xb000, v92
	v_lshl_add_u64 v[76:77], v[74:75], 0, v[4:5]
	global_load_lds_dwordx4 v[80:81], off
	v_lshl_add_u64 v[2:3], v[78:79], 0, s[6:7]
	s_mov_b32 m0, s42
	v_readfirstlane_b32 s16, v109
	v_add_u32_e32 v4, 0x4000, v92
	global_load_lds_dwordx4 v[2:3], off
	s_mov_b32 m0, s16
	v_readfirstlane_b32 s5, v4
	v_add_u32_e32 v4, 0xc000, v92
	global_load_lds_dwordx4 v[76:77], off
	v_lshl_add_u64 v[2:3], v[78:79], 0, s[98:99]
	s_mov_b32 m0, s5
	v_readfirstlane_b32 s6, v4
	v_add_u32_e32 v4, 0x5000, v92
	s_waitcnt vmcnt(0)
	s_waitcnt vmcnt(0) lgkmcnt(0)
	s_barrier
	v_mov_b32_e32 v2, 0
	v_mov_b32_e32 v3, 0
	v_mov_b32_e32 v4, 0
	v_mov_b32_e32 v5, 0
	v_mov_b32_e32 v6, 0
	v_mov_b32_e32 v7, 0
	v_mov_b32_e32 v8, 0
	v_mov_b32_e32 v9, 0
	v_mov_b32_e32 v10, 0
	v_mov_b32_e32 v11, 0
	v_mov_b32_e32 v12, 0
	v_mov_b32_e32 v13, 0
	v_mov_b32_e32 v14, 0
	v_mov_b32_e32 v15, 0
	v_mov_b32_e32 v16, 0
	v_mov_b32_e32 v17, 0
	v_mov_b32_e32 v18, 0
	v_mov_b32_e32 v19, 0
	v_mov_b32_e32 v20, 0
	v_mov_b32_e32 v21, 0
	v_mov_b32_e32 v22, 0
	v_mov_b32_e32 v23, 0
	v_mov_b32_e32 v24, 0
	v_mov_b32_e32 v25, 0
	v_mov_b32_e32 v26, 0
	v_mov_b32_e32 v27, 0
	v_mov_b32_e32 v28, 0
	v_mov_b32_e32 v29, 0
	v_mov_b32_e32 v30, 0
	v_mov_b32_e32 v31, 0
	v_mov_b32_e32 v32, 0
	v_mov_b32_e32 v33, 0
	v_mov_b32_e32 v34, 0
	v_mov_b32_e32 v35, 0
	v_mov_b32_e32 v36, 0
	v_mov_b32_e32 v37, 0
	v_mov_b32_e32 v38, 0
	v_mov_b32_e32 v39, 0
	v_mov_b32_e32 v40, 0
	v_mov_b32_e32 v41, 0
	v_mov_b32_e32 v42, 0
	v_mov_b32_e32 v43, 0
	v_mov_b32_e32 v44, 0
	v_mov_b32_e32 v45, 0
	v_mov_b32_e32 v46, 0
	v_mov_b32_e32 v47, 0
	v_mov_b32_e32 v48, 0
	v_mov_b32_e32 v49, 0
	v_mov_b32_e32 v50, 0
	v_mov_b32_e32 v51, 0
	v_mov_b32_e32 v52, 0
	v_mov_b32_e32 v53, 0
	v_mov_b32_e32 v54, 0
	v_mov_b32_e32 v55, 0
	v_mov_b32_e32 v56, 0
	v_mov_b32_e32 v57, 0
	v_mov_b32_e32 v58, 0
	v_mov_b32_e32 v59, 0
	v_mov_b32_e32 v60, 0
	v_mov_b32_e32 v61, 0
	v_mov_b32_e32 v62, 0
	v_mov_b32_e32 v63, 0
	v_mov_b32_e32 v64, 0
	v_mov_b32_e32 v65, 0
	v_mov_b32_e32 v132, 0
	v_mov_b32_e32 v133, 0
	v_mov_b32_e32 v134, 0
	v_mov_b32_e32 v135, 0
	v_mov_b32_e32 v136, 0
	v_mov_b32_e32 v137, 0
	v_mov_b32_e32 v138, 0
	v_mov_b32_e32 v139, 0
	v_mov_b32_e32 v140, 0
	v_mov_b32_e32 v141, 0
	v_mov_b32_e32 v142, 0
	v_mov_b32_e32 v143, 0
	v_mov_b32_e32 v144, 0
	v_mov_b32_e32 v145, 0
	v_mov_b32_e32 v146, 0
	v_mov_b32_e32 v147, 0
	v_mov_b32_e32 v148, 0
	v_mov_b32_e32 v149, 0
	v_mov_b32_e32 v150, 0
	v_mov_b32_e32 v151, 0
	v_mov_b32_e32 v152, 0
	v_mov_b32_e32 v153, 0
	v_mov_b32_e32 v154, 0
	v_mov_b32_e32 v155, 0
	v_mov_b32_e32 v156, 0
	v_mov_b32_e32 v157, 0
	v_mov_b32_e32 v158, 0
	v_mov_b32_e32 v159, 0
	v_mov_b32_e32 v160, 0
	v_mov_b32_e32 v161, 0
	v_mov_b32_e32 v162, 0
	v_mov_b32_e32 v163, 0
	v_mov_b32_e32 v164, 0
	v_mov_b32_e32 v165, 0
	v_mov_b32_e32 v166, 0
	v_mov_b32_e32 v167, 0
	v_mov_b32_e32 v168, 0
	v_mov_b32_e32 v169, 0
	v_mov_b32_e32 v170, 0
	v_mov_b32_e32 v171, 0
	v_mov_b32_e32 v172, 0
	v_mov_b32_e32 v173, 0
	v_mov_b32_e32 v174, 0
	v_mov_b32_e32 v175, 0
	v_mov_b32_e32 v176, 0
	v_mov_b32_e32 v177, 0
	v_mov_b32_e32 v178, 0
	v_mov_b32_e32 v179, 0
	v_mov_b32_e32 v180, 0
	v_mov_b32_e32 v181, 0
	v_mov_b32_e32 v182, 0
	v_mov_b32_e32 v183, 0
	v_mov_b32_e32 v184, 0
	v_mov_b32_e32 v185, 0
	v_mov_b32_e32 v186, 0
	v_mov_b32_e32 v187, 0
	v_mov_b32_e32 v188, 0
	v_mov_b32_e32 v189, 0
	v_mov_b32_e32 v190, 0
	v_mov_b32_e32 v191, 0
	v_mov_b32_e32 v192, 0
	v_mov_b32_e32 v193, 0
	v_mov_b32_e32 v194, 0
	v_mov_b32_e32 v195, 0
	v_lshl_add_u64 v[238:239], v[78:79], 0, s[98:99]
	s_mov_b64 s[10:11], 0x10080
	v_lshl_add_u64 v[240:241], v[78:79], 0, s[10:11]
	s_mov_b64 s[10:11], 0x20080
	v_lshl_add_u64 v[242:243], v[78:79], 0, s[10:11]
	s_mov_b64 s[10:11], 0x30080
	v_lshl_add_u64 v[244:245], v[78:79], 0, s[10:11]
	v_lshl_add_u64 v[246:247], v[84:85], 0, s[98:99]
	v_lshl_add_u64 v[248:249], v[82:83], 0, s[98:99]
	v_lshl_add_u64 v[250:251], v[80:81], 0, s[98:99]
	v_lshl_add_u64 v[118:119], v[76:77], 0, s[98:99]
	s_mov_b64 s[10:11], 0x20000
	v_lshl_add_u64 v[120:121], v[84:85], 0, s[10:11]
	v_lshl_add_u64 v[122:123], v[82:83], 0, s[10:11]
	v_lshl_add_u64 v[124:125], v[80:81], 0, s[10:11]
	v_lshl_add_u64 v[126:127], v[76:77], 0, s[10:11]
	v_add_u32_e32 v102, v96, v89
	v_add_u32_e32 v103, v95, v89
	v_add_u32_e32 v104, v94, v89
	v_add_u32_e32 v105, v87, v89
	v_add_u32_e32 v110, 0x10000, v102
	v_add_u32_e32 v111, 0x10000, v103
	v_add_u32_e32 v128, 0x10000, v104
	v_add_u32_e32 v129, 0x10000, v105
	s_add_u32 m0, s27, 0xc000
	s_nop 0
	global_load_lds_dwordx4 v[120:121], off
	v_lshl_add_u64 v[120:121], v[120:121], 0, s[98:99]
	s_add_u32 m0, s27, 0xd000
	s_nop 0
	global_load_lds_dwordx4 v[122:123], off
	v_lshl_add_u64 v[122:123], v[122:123], 0, s[98:99]
	s_add_u32 m0, s27, 0xe000
	s_nop 0
	global_load_lds_dwordx4 v[124:125], off
	v_lshl_add_u64 v[124:125], v[124:125], 0, s[98:99]
	s_add_u32 m0, s27, 0xf000
	s_nop 0
	global_load_lds_dwordx4 v[126:127], off
	v_lshl_add_u64 v[126:127], v[126:127], 0, s[98:99]
	ds_read_b128 v[206:209], v98
	ds_read_b128 v[210:213], v98 offset:4096
	ds_read_b128 v[214:217], v102 offset:32768
	ds_read_b128 v[218:221], v102 offset:40960
	ds_read_b128 v[222:225], v99
	ds_read_b128 v[226:229], v99 offset:4096
	ds_read_b128 v[230:233], v103 offset:32768
	ds_read_b128 v[234:237], v103 offset:40960
	s_waitcnt lgkmcnt(4)
	v_mfma_f32_32x32x16_bf16 v[34:49], v[206:209], v[214:217], v[34:49]
	s_add_u32 m0, s27, 0x10000
	s_nop 0
	global_load_lds_dwordx4 v[246:247], off
	v_lshl_add_u64 v[246:247], v[246:247], 0, s[98:99]
	v_mfma_f32_32x32x16_bf16 v[50:65], v[206:209], v[218:221], v[50:65]
	s_add_u32 m0, s27, 0x4000
	s_nop 0
	global_load_lds_dwordx4 v[238:239], off
	v_lshl_add_u64 v[238:239], v[238:239], 0, s[98:99]
	v_mfma_f32_32x32x16_bf16 v[2:17], v[210:213], v[214:217], v[2:17]
	s_add_u32 m0, s27, 0x11000
	s_nop 0
	global_load_lds_dwordx4 v[248:249], off
	v_lshl_add_u64 v[248:249], v[248:249], 0, s[98:99]
	v_mfma_f32_32x32x16_bf16 v[18:33], v[210:213], v[218:221], v[18:33]
	ds_read_b128 v[206:209], v100
	ds_read_b128 v[210:213], v100 offset:4096
	ds_read_b128 v[214:217], v104 offset:32768
	ds_read_b128 v[218:221], v104 offset:40960
	s_waitcnt lgkmcnt(4)
	v_mfma_f32_32x32x16_bf16 v[34:49], v[222:225], v[230:233], v[34:49]
	s_add_u32 m0, s27, 0x5000
	s_nop 0
	global_load_lds_dwordx4 v[240:241], off
	v_lshl_add_u64 v[240:241], v[240:241], 0, s[98:99]
	v_mfma_f32_32x32x16_bf16 v[50:65], v[222:225], v[234:237], v[50:65]
	s_add_u32 m0, s27, 0x12000
	s_nop 0
	global_load_lds_dwordx4 v[250:251], off
	v_lshl_add_u64 v[250:251], v[250:251], 0, s[98:99]
	v_mfma_f32_32x32x16_bf16 v[2:17], v[226:229], v[230:233], v[2:17]
	s_add_u32 m0, s27, 0x6000
	s_nop 0
	global_load_lds_dwordx4 v[242:243], off
	v_lshl_add_u64 v[242:243], v[242:243], 0, s[98:99]
	v_mfma_f32_32x32x16_bf16 v[18:33], v[226:229], v[234:237], v[18:33]
	ds_read_b128 v[222:225], v101
	ds_read_b128 v[226:229], v101 offset:4096
	ds_read_b128 v[230:233], v105 offset:32768
	ds_read_b128 v[234:237], v105 offset:40960
	s_waitcnt lgkmcnt(4)
	v_mfma_f32_32x32x16_bf16 v[34:49], v[206:209], v[214:217], v[34:49]
	s_add_u32 m0, s27, 0x13000
	s_nop 0
	global_load_lds_dwordx4 v[118:119], off
	v_lshl_add_u64 v[118:119], v[118:119], 0, s[98:99]
	v_mfma_f32_32x32x16_bf16 v[50:65], v[206:209], v[218:221], v[50:65]
	s_add_u32 m0, s27, 0x7000
	s_nop 0
	global_load_lds_dwordx4 v[244:245], off
	v_lshl_add_u64 v[244:245], v[244:245], 0, s[98:99]
	v_mfma_f32_32x32x16_bf16 v[2:17], v[210:213], v[214:217], v[2:17]
	v_mfma_f32_32x32x16_bf16 v[18:33], v[210:213], v[218:221], v[18:33]
	s_waitcnt vmcnt(8) lgkmcnt(0)
	s_barrier
	ds_read_b128 v[206:209], v98
	ds_read_b128 v[210:213], v98 offset:4096
	ds_read_b128 v[214:217], v102 offset:49152
	ds_read_b128 v[218:221], v102 offset:57344
	v_mfma_f32_32x32x16_bf16 v[34:49], v[222:225], v[230:233], v[34:49]
	v_mfma_f32_32x32x16_bf16 v[50:65], v[222:225], v[234:237], v[50:65]
	v_mfma_f32_32x32x16_bf16 v[2:17], v[226:229], v[230:233], v[2:17]
	v_mfma_f32_32x32x16_bf16 v[18:33], v[226:229], v[234:237], v[18:33]
	ds_read_b128 v[222:225], v99
	ds_read_b128 v[226:229], v99 offset:4096
	ds_read_b128 v[230:233], v103 offset:49152
	ds_read_b128 v[234:237], v103 offset:57344
	s_waitcnt lgkmcnt(4)
	v_mfma_f32_32x32x16_bf16 v[132:147], v[206:209], v[214:217], v[132:147]
	s_add_u32 m0, s27, 0x8000
	s_nop 0
	global_load_lds_dwordx4 v[120:121], off
	v_lshl_add_u64 v[120:121], v[120:121], 0, s[98:99]
	v_mfma_f32_32x32x16_bf16 v[148:163], v[206:209], v[218:221], v[148:163]
	s_add_u32 m0, s27, 0x9000
	s_nop 0
	global_load_lds_dwordx4 v[122:123], off
	v_lshl_add_u64 v[122:123], v[122:123], 0, s[98:99]
	v_mfma_f32_32x32x16_bf16 v[164:179], v[210:213], v[214:217], v[164:179]
	v_mfma_f32_32x32x16_bf16 v[180:195], v[210:213], v[218:221], v[180:195]
	ds_read_b128 v[206:209], v100
	ds_read_b128 v[210:213], v100 offset:4096
	ds_read_b128 v[214:217], v104 offset:49152
	ds_read_b128 v[218:221], v104 offset:57344
	s_waitcnt lgkmcnt(4)
	v_mfma_f32_32x32x16_bf16 v[132:147], v[222:225], v[230:233], v[132:147]
	s_add_u32 m0, s27, 0xa000
	s_nop 0
	global_load_lds_dwordx4 v[124:125], off
	v_lshl_add_u64 v[124:125], v[124:125], 0, s[98:99]
	v_mfma_f32_32x32x16_bf16 v[148:163], v[222:225], v[234:237], v[148:163]
	v_mfma_f32_32x32x16_bf16 v[164:179], v[226:229], v[230:233], v[164:179]
	v_mfma_f32_32x32x16_bf16 v[180:195], v[226:229], v[234:237], v[180:195]
	ds_read_b128 v[222:225], v101
	ds_read_b128 v[226:229], v101 offset:4096
	ds_read_b128 v[230:233], v105 offset:49152
	ds_read_b128 v[234:237], v105 offset:57344
	s_waitcnt lgkmcnt(4)
	v_mfma_f32_32x32x16_bf16 v[132:147], v[206:209], v[214:217], v[132:147]
	s_add_u32 m0, s27, 0xb000
	s_nop 0
	global_load_lds_dwordx4 v[126:127], off
	v_lshl_add_u64 v[126:127], v[126:127], 0, s[98:99]
	v_mfma_f32_32x32x16_bf16 v[148:163], v[206:209], v[218:221], v[148:163]
	v_mfma_f32_32x32x16_bf16 v[164:179], v[210:213], v[214:217], v[164:179]
	v_mfma_f32_32x32x16_bf16 v[180:195], v[210:213], v[218:221], v[180:195]
	s_waitcnt vmcnt(4) lgkmcnt(0)
	s_barrier
	ds_read_b128 v[206:209], v98 offset:16384
	ds_read_b128 v[210:213], v98 offset:20480
	ds_read_b128 v[214:217], v110
	ds_read_b128 v[218:221], v110 offset:8192
	v_mfma_f32_32x32x16_bf16 v[132:147], v[222:225], v[230:233], v[132:147]
	v_mfma_f32_32x32x16_bf16 v[148:163], v[222:225], v[234:237], v[148:163]
	v_mfma_f32_32x32x16_bf16 v[164:179], v[226:229], v[230:233], v[164:179]
	v_mfma_f32_32x32x16_bf16 v[180:195], v[226:229], v[234:237], v[180:195]
	ds_read_b128 v[222:225], v99 offset:16384
	ds_read_b128 v[226:229], v99 offset:20480
	ds_read_b128 v[230:233], v111
	ds_read_b128 v[234:237], v111 offset:8192
	s_waitcnt lgkmcnt(4)
	v_mfma_f32_32x32x16_bf16 v[34:49], v[206:209], v[214:217], v[34:49]
	s_add_u32 m0, s27, 0xc000
	s_nop 0
	global_load_lds_dwordx4 v[246:247], off
	v_lshl_add_u64 v[246:247], v[246:247], 0, s[98:99]
	v_mfma_f32_32x32x16_bf16 v[50:65], v[206:209], v[218:221], v[50:65]
	s_mov_b32 m0, s27
	s_nop 0
	global_load_lds_dwordx4 v[238:239], off
	v_lshl_add_u64 v[238:239], v[238:239], 0, s[98:99]
	v_mfma_f32_32x32x16_bf16 v[2:17], v[210:213], v[214:217], v[2:17]
	s_add_u32 m0, s27, 0xd000
	s_nop 0
	global_load_lds_dwordx4 v[248:249], off
	v_lshl_add_u64 v[248:249], v[248:249], 0, s[98:99]
	v_mfma_f32_32x32x16_bf16 v[18:33], v[210:213], v[218:221], v[18:33]
	ds_read_b128 v[206:209], v100 offset:16384
	ds_read_b128 v[210:213], v100 offset:20480
	ds_read_b128 v[214:217], v128
	ds_read_b128 v[218:221], v128 offset:8192
	s_waitcnt lgkmcnt(4)
	v_mfma_f32_32x32x16_bf16 v[34:49], v[222:225], v[230:233], v[34:49]
	s_add_u32 m0, s27, 0x1000
	s_nop 0
	global_load_lds_dwordx4 v[240:241], off
	v_lshl_add_u64 v[240:241], v[240:241], 0, s[98:99]
	v_mfma_f32_32x32x16_bf16 v[50:65], v[222:225], v[234:237], v[50:65]
	s_add_u32 m0, s27, 0xe000
	s_nop 0
	global_load_lds_dwordx4 v[250:251], off
	v_lshl_add_u64 v[250:251], v[250:251], 0, s[98:99]
	v_mfma_f32_32x32x16_bf16 v[2:17], v[226:229], v[230:233], v[2:17]
	s_add_u32 m0, s27, 0x2000
	s_nop 0
	global_load_lds_dwordx4 v[242:243], off
	v_lshl_add_u64 v[242:243], v[242:243], 0, s[98:99]
	v_mfma_f32_32x32x16_bf16 v[18:33], v[226:229], v[234:237], v[18:33]
	ds_read_b128 v[222:225], v101 offset:16384
	ds_read_b128 v[226:229], v101 offset:20480
	ds_read_b128 v[230:233], v129
	ds_read_b128 v[234:237], v129 offset:8192
	s_waitcnt lgkmcnt(4)
	v_mfma_f32_32x32x16_bf16 v[34:49], v[206:209], v[214:217], v[34:49]
	s_add_u32 m0, s27, 0xf000
	s_nop 0
	global_load_lds_dwordx4 v[118:119], off
	v_lshl_add_u64 v[118:119], v[118:119], 0, s[98:99]
	v_mfma_f32_32x32x16_bf16 v[50:65], v[206:209], v[218:221], v[50:65]
	s_add_u32 m0, s27, 0x3000
	s_nop 0
	global_load_lds_dwordx4 v[244:245], off
	v_lshl_add_u64 v[244:245], v[244:245], 0, s[98:99]
	v_mfma_f32_32x32x16_bf16 v[2:17], v[210:213], v[214:217], v[2:17]
	v_mfma_f32_32x32x16_bf16 v[18:33], v[210:213], v[218:221], v[18:33]
	s_waitcnt vmcnt(8) lgkmcnt(0)
	s_barrier
	ds_read_b128 v[206:209], v98 offset:16384
	ds_read_b128 v[210:213], v98 offset:20480
	ds_read_b128 v[214:217], v102 offset:32768
	ds_read_b128 v[218:221], v102 offset:40960
	v_mfma_f32_32x32x16_bf16 v[34:49], v[222:225], v[230:233], v[34:49]
	v_mfma_f32_32x32x16_bf16 v[50:65], v[222:225], v[234:237], v[50:65]
	v_mfma_f32_32x32x16_bf16 v[2:17], v[226:229], v[230:233], v[2:17]
	v_mfma_f32_32x32x16_bf16 v[18:33], v[226:229], v[234:237], v[18:33]
	ds_read_b128 v[222:225], v99 offset:16384
	ds_read_b128 v[226:229], v99 offset:20480
	ds_read_b128 v[230:233], v103 offset:32768
	ds_read_b128 v[234:237], v103 offset:40960
	s_waitcnt lgkmcnt(4)
	v_mfma_f32_32x32x16_bf16 v[132:147], v[206:209], v[214:217], v[132:147]
	s_add_u32 m0, s27, 0x10000
	s_nop 0
	global_load_lds_dwordx4 v[120:121], off
	v_lshl_add_u64 v[120:121], v[120:121], 0, s[98:99]
	v_mfma_f32_32x32x16_bf16 v[148:163], v[206:209], v[218:221], v[148:163]
	s_add_u32 m0, s27, 0x11000
	s_nop 0
	global_load_lds_dwordx4 v[122:123], off
	v_lshl_add_u64 v[122:123], v[122:123], 0, s[98:99]
	v_mfma_f32_32x32x16_bf16 v[164:179], v[210:213], v[214:217], v[164:179]
	v_mfma_f32_32x32x16_bf16 v[180:195], v[210:213], v[218:221], v[180:195]
	ds_read_b128 v[206:209], v100 offset:16384
	ds_read_b128 v[210:213], v100 offset:20480
	ds_read_b128 v[214:217], v104 offset:32768
	ds_read_b128 v[218:221], v104 offset:40960
	s_waitcnt lgkmcnt(4)
	v_mfma_f32_32x32x16_bf16 v[132:147], v[222:225], v[230:233], v[132:147]
	s_add_u32 m0, s27, 0x12000
	s_nop 0
	global_load_lds_dwordx4 v[124:125], off
	v_lshl_add_u64 v[124:125], v[124:125], 0, s[98:99]
	v_mfma_f32_32x32x16_bf16 v[148:163], v[222:225], v[234:237], v[148:163]
	v_mfma_f32_32x32x16_bf16 v[164:179], v[226:229], v[230:233], v[164:179]
	v_mfma_f32_32x32x16_bf16 v[180:195], v[226:229], v[234:237], v[180:195]
	ds_read_b128 v[222:225], v101 offset:16384
	ds_read_b128 v[226:229], v101 offset:20480
	ds_read_b128 v[230:233], v105 offset:32768
	ds_read_b128 v[234:237], v105 offset:40960
	s_waitcnt lgkmcnt(4)
	v_mfma_f32_32x32x16_bf16 v[132:147], v[206:209], v[214:217], v[132:147]
	s_add_u32 m0, s27, 0x13000
	s_nop 0
	global_load_lds_dwordx4 v[126:127], off
	v_lshl_add_u64 v[126:127], v[126:127], 0, s[98:99]
	v_mfma_f32_32x32x16_bf16 v[148:163], v[206:209], v[218:221], v[148:163]
	v_mfma_f32_32x32x16_bf16 v[164:179], v[210:213], v[214:217], v[164:179]
	v_mfma_f32_32x32x16_bf16 v[180:195], v[210:213], v[218:221], v[180:195]
	s_waitcnt vmcnt(4) lgkmcnt(0)
	s_barrier
	ds_read_b128 v[206:209], v98
	ds_read_b128 v[210:213], v98 offset:4096
	ds_read_b128 v[214:217], v102 offset:49152
	ds_read_b128 v[218:221], v102 offset:57344
	v_mfma_f32_32x32x16_bf16 v[132:147], v[222:225], v[230:233], v[132:147]
	v_mfma_f32_32x32x16_bf16 v[148:163], v[222:225], v[234:237], v[148:163]
	v_mfma_f32_32x32x16_bf16 v[164:179], v[226:229], v[230:233], v[164:179]
	v_mfma_f32_32x32x16_bf16 v[180:195], v[226:229], v[234:237], v[180:195]
	ds_read_b128 v[222:225], v99
	ds_read_b128 v[226:229], v99 offset:4096
	ds_read_b128 v[230:233], v103 offset:49152
	ds_read_b128 v[234:237], v103 offset:57344
	s_waitcnt lgkmcnt(4)
	v_mfma_f32_32x32x16_bf16 v[34:49], v[206:209], v[214:217], v[34:49]
	s_add_u32 m0, s27, 0x8000
	s_nop 0
	global_load_lds_dwordx4 v[246:247], off
	v_lshl_add_u64 v[246:247], v[246:247], 0, s[98:99]
	v_mfma_f32_32x32x16_bf16 v[50:65], v[206:209], v[218:221], v[50:65]
	s_add_u32 m0, s27, 0x4000
	s_nop 0
	global_load_lds_dwordx4 v[238:239], off
	v_lshl_add_u64 v[238:239], v[238:239], 0, s[98:99]
	v_mfma_f32_32x32x16_bf16 v[2:17], v[210:213], v[214:217], v[2:17]
	s_add_u32 m0, s27, 0x9000
	s_nop 0
	global_load_lds_dwordx4 v[248:249], off
	v_lshl_add_u64 v[248:249], v[248:249], 0, s[98:99]
	v_mfma_f32_32x32x16_bf16 v[18:33], v[210:213], v[218:221], v[18:33]
	ds_read_b128 v[206:209], v100
	ds_read_b128 v[210:213], v100 offset:4096
	ds_read_b128 v[214:217], v104 offset:49152
	ds_read_b128 v[218:221], v104 offset:57344
	s_waitcnt lgkmcnt(4)
	v_mfma_f32_32x32x16_bf16 v[34:49], v[222:225], v[230:233], v[34:49]
	s_add_u32 m0, s27, 0x5000
	s_nop 0
	global_load_lds_dwordx4 v[240:241], off
	v_lshl_add_u64 v[240:241], v[240:241], 0, s[98:99]
	v_mfma_f32_32x32x16_bf16 v[50:65], v[222:225], v[234:237], v[50:65]
	s_add_u32 m0, s27, 0xa000
	s_nop 0
	global_load_lds_dwordx4 v[250:251], off
	v_lshl_add_u64 v[250:251], v[250:251], 0, s[98:99]
	v_mfma_f32_32x32x16_bf16 v[2:17], v[226:229], v[230:233], v[2:17]
	s_add_u32 m0, s27, 0x6000
	s_nop 0
	global_load_lds_dwordx4 v[242:243], off
	v_lshl_add_u64 v[242:243], v[242:243], 0, s[98:99]
	v_mfma_f32_32x32x16_bf16 v[18:33], v[226:229], v[234:237], v[18:33]
	ds_read_b128 v[222:225], v101
	ds_read_b128 v[226:229], v101 offset:4096
	ds_read_b128 v[230:233], v105 offset:49152
	ds_read_b128 v[234:237], v105 offset:57344
	s_waitcnt lgkmcnt(4)
	v_mfma_f32_32x32x16_bf16 v[34:49], v[206:209], v[214:217], v[34:49]
	s_add_u32 m0, s27, 0xb000
	s_nop 0
	global_load_lds_dwordx4 v[118:119], off
	v_lshl_add_u64 v[118:119], v[118:119], 0, s[98:99]
	v_mfma_f32_32x32x16_bf16 v[50:65], v[206:209], v[218:221], v[50:65]
	s_add_u32 m0, s27, 0x7000
	s_nop 0
	global_load_lds_dwordx4 v[244:245], off
	v_lshl_add_u64 v[244:245], v[244:245], 0, s[98:99]
	v_mfma_f32_32x32x16_bf16 v[2:17], v[210:213], v[214:217], v[2:17]
	v_mfma_f32_32x32x16_bf16 v[18:33], v[210:213], v[218:221], v[18:33]
	s_waitcnt vmcnt(8) lgkmcnt(0)
	s_barrier
	ds_read_b128 v[206:209], v98
	ds_read_b128 v[210:213], v98 offset:4096
	ds_read_b128 v[214:217], v110
	ds_read_b128 v[218:221], v110 offset:8192
	v_mfma_f32_32x32x16_bf16 v[34:49], v[222:225], v[230:233], v[34:49]
	v_mfma_f32_32x32x16_bf16 v[50:65], v[222:225], v[234:237], v[50:65]
	v_mfma_f32_32x32x16_bf16 v[2:17], v[226:229], v[230:233], v[2:17]
	v_mfma_f32_32x32x16_bf16 v[18:33], v[226:229], v[234:237], v[18:33]
	ds_read_b128 v[222:225], v99
	ds_read_b128 v[226:229], v99 offset:4096
	ds_read_b128 v[230:233], v111
	ds_read_b128 v[234:237], v111 offset:8192
	s_waitcnt lgkmcnt(4)
	v_mfma_f32_32x32x16_bf16 v[132:147], v[206:209], v[214:217], v[132:147]
	s_add_u32 m0, s27, 0xc000
	s_nop 0
	global_load_lds_dwordx4 v[120:121], off
	v_lshl_add_u64 v[120:121], v[120:121], 0, s[98:99]
	v_mfma_f32_32x32x16_bf16 v[148:163], v[206:209], v[218:221], v[148:163]
	s_add_u32 m0, s27, 0xd000
	s_nop 0
	global_load_lds_dwordx4 v[122:123], off
	v_lshl_add_u64 v[122:123], v[122:123], 0, s[98:99]
	v_mfma_f32_32x32x16_bf16 v[164:179], v[210:213], v[214:217], v[164:179]
	v_mfma_f32_32x32x16_bf16 v[180:195], v[210:213], v[218:221], v[180:195]
	ds_read_b128 v[206:209], v100
	ds_read_b128 v[210:213], v100 offset:4096
	ds_read_b128 v[214:217], v128
	ds_read_b128 v[218:221], v128 offset:8192
	s_waitcnt lgkmcnt(4)
	v_mfma_f32_32x32x16_bf16 v[132:147], v[222:225], v[230:233], v[132:147]
	s_add_u32 m0, s27, 0xe000
	s_nop 0
	global_load_lds_dwordx4 v[124:125], off
	v_lshl_add_u64 v[124:125], v[124:125], 0, s[98:99]
	v_mfma_f32_32x32x16_bf16 v[148:163], v[222:225], v[234:237], v[148:163]
	v_mfma_f32_32x32x16_bf16 v[164:179], v[226:229], v[230:233], v[164:179]
	v_mfma_f32_32x32x16_bf16 v[180:195], v[226:229], v[234:237], v[180:195]
	ds_read_b128 v[222:225], v101
	ds_read_b128 v[226:229], v101 offset:4096
	ds_read_b128 v[230:233], v129
	ds_read_b128 v[234:237], v129 offset:8192
	s_waitcnt lgkmcnt(4)
	v_mfma_f32_32x32x16_bf16 v[132:147], v[206:209], v[214:217], v[132:147]
	s_add_u32 m0, s27, 0xf000
	s_nop 0
	global_load_lds_dwordx4 v[126:127], off
	v_lshl_add_u64 v[126:127], v[126:127], 0, s[98:99]
	v_mfma_f32_32x32x16_bf16 v[148:163], v[206:209], v[218:221], v[148:163]
	v_mfma_f32_32x32x16_bf16 v[164:179], v[210:213], v[214:217], v[164:179]
	v_mfma_f32_32x32x16_bf16 v[180:195], v[210:213], v[218:221], v[180:195]
	s_waitcnt vmcnt(4) lgkmcnt(0)
	s_barrier
	ds_read_b128 v[206:209], v98 offset:16384
	ds_read_b128 v[210:213], v98 offset:20480
	ds_read_b128 v[214:217], v102 offset:32768
	ds_read_b128 v[218:221], v102 offset:40960
	v_mfma_f32_32x32x16_bf16 v[132:147], v[222:225], v[230:233], v[132:147]
	v_mfma_f32_32x32x16_bf16 v[148:163], v[222:225], v[234:237], v[148:163]
	v_mfma_f32_32x32x16_bf16 v[164:179], v[226:229], v[230:233], v[164:179]
	v_mfma_f32_32x32x16_bf16 v[180:195], v[226:229], v[234:237], v[180:195]
	ds_read_b128 v[222:225], v99 offset:16384
	ds_read_b128 v[226:229], v99 offset:20480
	ds_read_b128 v[230:233], v103 offset:32768
	ds_read_b128 v[234:237], v103 offset:40960
	s_waitcnt lgkmcnt(4)
	v_mfma_f32_32x32x16_bf16 v[34:49], v[206:209], v[214:217], v[34:49]
	s_add_u32 m0, s27, 0x10000
	s_nop 0
	global_load_lds_dwordx4 v[246:247], off
	v_lshl_add_u64 v[246:247], v[246:247], 0, s[98:99]
	v_mfma_f32_32x32x16_bf16 v[50:65], v[206:209], v[218:221], v[50:65]
	s_mov_b32 m0, s27
	s_nop 0
	global_load_lds_dwordx4 v[238:239], off
	v_lshl_add_u64 v[238:239], v[238:239], 0, s[98:99]
	v_mfma_f32_32x32x16_bf16 v[2:17], v[210:213], v[214:217], v[2:17]
	s_add_u32 m0, s27, 0x11000
	s_nop 0
	global_load_lds_dwordx4 v[248:249], off
	v_lshl_add_u64 v[248:249], v[248:249], 0, s[98:99]
	v_mfma_f32_32x32x16_bf16 v[18:33], v[210:213], v[218:221], v[18:33]
	ds_read_b128 v[206:209], v100 offset:16384
	ds_read_b128 v[210:213], v100 offset:20480
	ds_read_b128 v[214:217], v104 offset:32768
	ds_read_b128 v[218:221], v104 offset:40960
	s_waitcnt lgkmcnt(4)
	v_mfma_f32_32x32x16_bf16 v[34:49], v[222:225], v[230:233], v[34:49]
	s_add_u32 m0, s27, 0x1000
	s_nop 0
	global_load_lds_dwordx4 v[240:241], off
	v_lshl_add_u64 v[240:241], v[240:241], 0, s[98:99]
	v_mfma_f32_32x32x16_bf16 v[50:65], v[222:225], v[234:237], v[50:65]
	s_add_u32 m0, s27, 0x12000
	s_nop 0
	global_load_lds_dwordx4 v[250:251], off
	v_lshl_add_u64 v[250:251], v[250:251], 0, s[98:99]
	v_mfma_f32_32x32x16_bf16 v[2:17], v[226:229], v[230:233], v[2:17]
	s_add_u32 m0, s27, 0x2000
	s_nop 0
	global_load_lds_dwordx4 v[242:243], off
	v_lshl_add_u64 v[242:243], v[242:243], 0, s[98:99]
	v_mfma_f32_32x32x16_bf16 v[18:33], v[226:229], v[234:237], v[18:33]
	ds_read_b128 v[222:225], v101 offset:16384
	ds_read_b128 v[226:229], v101 offset:20480
	ds_read_b128 v[230:233], v105 offset:32768
	ds_read_b128 v[234:237], v105 offset:40960
	s_waitcnt lgkmcnt(4)
	v_mfma_f32_32x32x16_bf16 v[34:49], v[206:209], v[214:217], v[34:49]
	s_add_u32 m0, s27, 0x13000
	s_nop 0
	global_load_lds_dwordx4 v[118:119], off
	v_lshl_add_u64 v[118:119], v[118:119], 0, s[98:99]
	v_mfma_f32_32x32x16_bf16 v[50:65], v[206:209], v[218:221], v[50:65]
	s_add_u32 m0, s27, 0x3000
	s_nop 0
	global_load_lds_dwordx4 v[244:245], off
	v_lshl_add_u64 v[244:245], v[244:245], 0, s[98:99]
	v_mfma_f32_32x32x16_bf16 v[2:17], v[210:213], v[214:217], v[2:17]
	v_mfma_f32_32x32x16_bf16 v[18:33], v[210:213], v[218:221], v[18:33]
	s_waitcnt vmcnt(8) lgkmcnt(0)
	s_barrier
	ds_read_b128 v[206:209], v98 offset:16384
	ds_read_b128 v[210:213], v98 offset:20480
	ds_read_b128 v[214:217], v102 offset:49152
	ds_read_b128 v[218:221], v102 offset:57344
	v_mfma_f32_32x32x16_bf16 v[34:49], v[222:225], v[230:233], v[34:49]
	v_mfma_f32_32x32x16_bf16 v[50:65], v[222:225], v[234:237], v[50:65]
	v_mfma_f32_32x32x16_bf16 v[2:17], v[226:229], v[230:233], v[2:17]
	v_mfma_f32_32x32x16_bf16 v[18:33], v[226:229], v[234:237], v[18:33]
	ds_read_b128 v[222:225], v99 offset:16384
	ds_read_b128 v[226:229], v99 offset:20480
	ds_read_b128 v[230:233], v103 offset:49152
	ds_read_b128 v[234:237], v103 offset:57344
	s_waitcnt lgkmcnt(4)
	v_mfma_f32_32x32x16_bf16 v[132:147], v[206:209], v[214:217], v[132:147]
	s_add_u32 m0, s27, 0x8000
	s_nop 0
	global_load_lds_dwordx4 v[120:121], off
	v_lshl_add_u64 v[120:121], v[120:121], 0, s[98:99]
	v_mfma_f32_32x32x16_bf16 v[148:163], v[206:209], v[218:221], v[148:163]
	s_add_u32 m0, s27, 0x9000
	s_nop 0
	global_load_lds_dwordx4 v[122:123], off
	v_lshl_add_u64 v[122:123], v[122:123], 0, s[98:99]
	v_mfma_f32_32x32x16_bf16 v[164:179], v[210:213], v[214:217], v[164:179]
	v_mfma_f32_32x32x16_bf16 v[180:195], v[210:213], v[218:221], v[180:195]
	ds_read_b128 v[206:209], v100 offset:16384
	ds_read_b128 v[210:213], v100 offset:20480
	ds_read_b128 v[214:217], v104 offset:49152
	ds_read_b128 v[218:221], v104 offset:57344
	s_waitcnt lgkmcnt(4)
	v_mfma_f32_32x32x16_bf16 v[132:147], v[222:225], v[230:233], v[132:147]
	s_add_u32 m0, s27, 0xa000
	s_nop 0
	global_load_lds_dwordx4 v[124:125], off
	v_lshl_add_u64 v[124:125], v[124:125], 0, s[98:99]
	v_mfma_f32_32x32x16_bf16 v[148:163], v[222:225], v[234:237], v[148:163]
	v_mfma_f32_32x32x16_bf16 v[164:179], v[226:229], v[230:233], v[164:179]
	v_mfma_f32_32x32x16_bf16 v[180:195], v[226:229], v[234:237], v[180:195]
	ds_read_b128 v[222:225], v101 offset:16384
	ds_read_b128 v[226:229], v101 offset:20480
	ds_read_b128 v[230:233], v105 offset:49152
	ds_read_b128 v[234:237], v105 offset:57344
	s_waitcnt lgkmcnt(4)
	v_mfma_f32_32x32x16_bf16 v[132:147], v[206:209], v[214:217], v[132:147]
	s_add_u32 m0, s27, 0xb000
	s_nop 0
	global_load_lds_dwordx4 v[126:127], off
	v_lshl_add_u64 v[126:127], v[126:127], 0, s[98:99]
	v_mfma_f32_32x32x16_bf16 v[148:163], v[206:209], v[218:221], v[148:163]
	v_mfma_f32_32x32x16_bf16 v[164:179], v[210:213], v[214:217], v[164:179]
	v_mfma_f32_32x32x16_bf16 v[180:195], v[210:213], v[218:221], v[180:195]
	s_waitcnt vmcnt(4) lgkmcnt(0)
	s_barrier
	ds_read_b128 v[206:209], v98
	ds_read_b128 v[210:213], v98 offset:4096
	ds_read_b128 v[214:217], v110
	ds_read_b128 v[218:221], v110 offset:8192
	v_mfma_f32_32x32x16_bf16 v[132:147], v[222:225], v[230:233], v[132:147]
	v_mfma_f32_32x32x16_bf16 v[148:163], v[222:225], v[234:237], v[148:163]
	v_mfma_f32_32x32x16_bf16 v[164:179], v[226:229], v[230:233], v[164:179]
	v_mfma_f32_32x32x16_bf16 v[180:195], v[226:229], v[234:237], v[180:195]
	ds_read_b128 v[222:225], v99
	ds_read_b128 v[226:229], v99 offset:4096
	ds_read_b128 v[230:233], v111
	ds_read_b128 v[234:237], v111 offset:8192
	s_waitcnt lgkmcnt(4)
	v_mfma_f32_32x32x16_bf16 v[34:49], v[206:209], v[214:217], v[34:49]
	s_add_u32 m0, s27, 0xc000
	s_nop 0
	global_load_lds_dwordx4 v[246:247], off
	v_lshl_add_u64 v[246:247], v[246:247], 0, s[98:99]
	v_mfma_f32_32x32x16_bf16 v[50:65], v[206:209], v[218:221], v[50:65]
	s_add_u32 m0, s27, 0x4000
	s_nop 0
	global_load_lds_dwordx4 v[238:239], off
	v_lshl_add_u64 v[238:239], v[238:239], 0, s[98:99]
	v_mfma_f32_32x32x16_bf16 v[2:17], v[210:213], v[214:217], v[2:17]
	s_add_u32 m0, s27, 0xd000
	s_nop 0
	global_load_lds_dwordx4 v[248:249], off
	v_lshl_add_u64 v[248:249], v[248:249], 0, s[98:99]
	v_mfma_f32_32x32x16_bf16 v[18:33], v[210:213], v[218:221], v[18:33]
	ds_read_b128 v[206:209], v100
	ds_read_b128 v[210:213], v100 offset:4096
	ds_read_b128 v[214:217], v128
	ds_read_b128 v[218:221], v128 offset:8192
	s_waitcnt lgkmcnt(4)
	v_mfma_f32_32x32x16_bf16 v[34:49], v[222:225], v[230:233], v[34:49]
	s_add_u32 m0, s27, 0x5000
	s_nop 0
	global_load_lds_dwordx4 v[240:241], off
	v_lshl_add_u64 v[240:241], v[240:241], 0, s[98:99]
	v_mfma_f32_32x32x16_bf16 v[50:65], v[222:225], v[234:237], v[50:65]
	s_add_u32 m0, s27, 0xe000
	s_nop 0
	global_load_lds_dwordx4 v[250:251], off
	v_lshl_add_u64 v[250:251], v[250:251], 0, s[98:99]
	v_mfma_f32_32x32x16_bf16 v[2:17], v[226:229], v[230:233], v[2:17]
	s_add_u32 m0, s27, 0x6000
	s_nop 0
	global_load_lds_dwordx4 v[242:243], off
	v_lshl_add_u64 v[242:243], v[242:243], 0, s[98:99]
	v_mfma_f32_32x32x16_bf16 v[18:33], v[226:229], v[234:237], v[18:33]
	ds_read_b128 v[222:225], v101
	ds_read_b128 v[226:229], v101 offset:4096
	ds_read_b128 v[230:233], v129
	ds_read_b128 v[234:237], v129 offset:8192
	s_waitcnt lgkmcnt(4)
	v_mfma_f32_32x32x16_bf16 v[34:49], v[206:209], v[214:217], v[34:49]
	s_add_u32 m0, s27, 0xf000
	s_nop 0
	global_load_lds_dwordx4 v[118:119], off
	v_lshl_add_u64 v[118:119], v[118:119], 0, s[98:99]
	v_mfma_f32_32x32x16_bf16 v[50:65], v[206:209], v[218:221], v[50:65]
	s_add_u32 m0, s27, 0x7000
	s_nop 0
	global_load_lds_dwordx4 v[244:245], off
	v_lshl_add_u64 v[244:245], v[244:245], 0, s[98:99]
	v_mfma_f32_32x32x16_bf16 v[2:17], v[210:213], v[214:217], v[2:17]
	v_mfma_f32_32x32x16_bf16 v[18:33], v[210:213], v[218:221], v[18:33]
	s_waitcnt vmcnt(8) lgkmcnt(0)
	s_barrier
	ds_read_b128 v[206:209], v98
	ds_read_b128 v[210:213], v98 offset:4096
	ds_read_b128 v[214:217], v102 offset:32768
	ds_read_b128 v[218:221], v102 offset:40960
	v_mfma_f32_32x32x16_bf16 v[34:49], v[222:225], v[230:233], v[34:49]
	v_mfma_f32_32x32x16_bf16 v[50:65], v[222:225], v[234:237], v[50:65]
	v_mfma_f32_32x32x16_bf16 v[2:17], v[226:229], v[230:233], v[2:17]
	v_mfma_f32_32x32x16_bf16 v[18:33], v[226:229], v[234:237], v[18:33]
	ds_read_b128 v[222:225], v99
	ds_read_b128 v[226:229], v99 offset:4096
	ds_read_b128 v[230:233], v103 offset:32768
	ds_read_b128 v[234:237], v103 offset:40960
	s_waitcnt lgkmcnt(4)
	v_mfma_f32_32x32x16_bf16 v[132:147], v[206:209], v[214:217], v[132:147]
	s_add_u32 m0, s27, 0x10000
	s_nop 0
	global_load_lds_dwordx4 v[120:121], off
	v_lshl_add_u64 v[120:121], v[120:121], 0, s[98:99]
	v_mfma_f32_32x32x16_bf16 v[148:163], v[206:209], v[218:221], v[148:163]
	s_add_u32 m0, s27, 0x11000
	s_nop 0
	global_load_lds_dwordx4 v[122:123], off
	v_lshl_add_u64 v[122:123], v[122:123], 0, s[98:99]
	v_mfma_f32_32x32x16_bf16 v[164:179], v[210:213], v[214:217], v[164:179]
	v_mfma_f32_32x32x16_bf16 v[180:195], v[210:213], v[218:221], v[180:195]
	ds_read_b128 v[206:209], v100
	ds_read_b128 v[210:213], v100 offset:4096
	ds_read_b128 v[214:217], v104 offset:32768
	ds_read_b128 v[218:221], v104 offset:40960
	s_waitcnt lgkmcnt(4)
	v_mfma_f32_32x32x16_bf16 v[132:147], v[222:225], v[230:233], v[132:147]
	s_add_u32 m0, s27, 0x12000
	s_nop 0
	global_load_lds_dwordx4 v[124:125], off
	v_lshl_add_u64 v[124:125], v[124:125], 0, s[98:99]
	v_mfma_f32_32x32x16_bf16 v[148:163], v[222:225], v[234:237], v[148:163]
	v_mfma_f32_32x32x16_bf16 v[164:179], v[226:229], v[230:233], v[164:179]
	v_mfma_f32_32x32x16_bf16 v[180:195], v[226:229], v[234:237], v[180:195]
	ds_read_b128 v[222:225], v101
	ds_read_b128 v[226:229], v101 offset:4096
	ds_read_b128 v[230:233], v105 offset:32768
	ds_read_b128 v[234:237], v105 offset:40960
	s_waitcnt lgkmcnt(4)
	v_mfma_f32_32x32x16_bf16 v[132:147], v[206:209], v[214:217], v[132:147]
	s_add_u32 m0, s27, 0x13000
	s_nop 0
	global_load_lds_dwordx4 v[126:127], off
	v_lshl_add_u64 v[126:127], v[126:127], 0, s[98:99]
	v_mfma_f32_32x32x16_bf16 v[148:163], v[206:209], v[218:221], v[148:163]
	v_mfma_f32_32x32x16_bf16 v[164:179], v[210:213], v[214:217], v[164:179]
	v_mfma_f32_32x32x16_bf16 v[180:195], v[210:213], v[218:221], v[180:195]
	s_waitcnt vmcnt(4) lgkmcnt(0)
	s_barrier
	ds_read_b128 v[206:209], v98 offset:16384
	ds_read_b128 v[210:213], v98 offset:20480
	ds_read_b128 v[214:217], v102 offset:49152
	ds_read_b128 v[218:221], v102 offset:57344
	v_mfma_f32_32x32x16_bf16 v[132:147], v[222:225], v[230:233], v[132:147]
	v_mfma_f32_32x32x16_bf16 v[148:163], v[222:225], v[234:237], v[148:163]
	v_mfma_f32_32x32x16_bf16 v[164:179], v[226:229], v[230:233], v[164:179]
	v_mfma_f32_32x32x16_bf16 v[180:195], v[226:229], v[234:237], v[180:195]
	ds_read_b128 v[222:225], v99 offset:16384
	ds_read_b128 v[226:229], v99 offset:20480
	ds_read_b128 v[230:233], v103 offset:49152
	ds_read_b128 v[234:237], v103 offset:57344
	s_waitcnt lgkmcnt(4)
	v_mfma_f32_32x32x16_bf16 v[34:49], v[206:209], v[214:217], v[34:49]
	s_add_u32 m0, s27, 0x8000
	s_nop 0
	global_load_lds_dwordx4 v[246:247], off
	v_lshl_add_u64 v[246:247], v[246:247], 0, s[98:99]
	v_mfma_f32_32x32x16_bf16 v[50:65], v[206:209], v[218:221], v[50:65]
	s_mov_b32 m0, s27
	s_nop 0
	global_load_lds_dwordx4 v[238:239], off
	v_lshl_add_u64 v[238:239], v[238:239], 0, s[98:99]
	v_mfma_f32_32x32x16_bf16 v[2:17], v[210:213], v[214:217], v[2:17]
	s_add_u32 m0, s27, 0x9000
	s_nop 0
	global_load_lds_dwordx4 v[248:249], off
	v_lshl_add_u64 v[248:249], v[248:249], 0, s[98:99]
	v_mfma_f32_32x32x16_bf16 v[18:33], v[210:213], v[218:221], v[18:33]
	ds_read_b128 v[206:209], v100 offset:16384
	ds_read_b128 v[210:213], v100 offset:20480
	ds_read_b128 v[214:217], v104 offset:49152
	ds_read_b128 v[218:221], v104 offset:57344
	s_waitcnt lgkmcnt(4)
	v_mfma_f32_32x32x16_bf16 v[34:49], v[222:225], v[230:233], v[34:49]
	s_add_u32 m0, s27, 0x1000
	s_nop 0
	global_load_lds_dwordx4 v[240:241], off
	v_lshl_add_u64 v[240:241], v[240:241], 0, s[98:99]
	v_mfma_f32_32x32x16_bf16 v[50:65], v[222:225], v[234:237], v[50:65]
	s_add_u32 m0, s27, 0xa000
	s_nop 0
	global_load_lds_dwordx4 v[250:251], off
	v_lshl_add_u64 v[250:251], v[250:251], 0, s[98:99]
	v_mfma_f32_32x32x16_bf16 v[2:17], v[226:229], v[230:233], v[2:17]
	s_add_u32 m0, s27, 0x2000
	s_nop 0
	global_load_lds_dwordx4 v[242:243], off
	v_lshl_add_u64 v[242:243], v[242:243], 0, s[98:99]
	v_mfma_f32_32x32x16_bf16 v[18:33], v[226:229], v[234:237], v[18:33]
	ds_read_b128 v[222:225], v101 offset:16384
	ds_read_b128 v[226:229], v101 offset:20480
	ds_read_b128 v[230:233], v105 offset:49152
	ds_read_b128 v[234:237], v105 offset:57344
	s_waitcnt lgkmcnt(4)
	v_mfma_f32_32x32x16_bf16 v[34:49], v[206:209], v[214:217], v[34:49]
	s_add_u32 m0, s27, 0xb000
	s_nop 0
	global_load_lds_dwordx4 v[118:119], off
	v_lshl_add_u64 v[118:119], v[118:119], 0, s[98:99]
	v_mfma_f32_32x32x16_bf16 v[50:65], v[206:209], v[218:221], v[50:65]
	s_add_u32 m0, s27, 0x3000
	s_nop 0
	global_load_lds_dwordx4 v[244:245], off
	v_lshl_add_u64 v[244:245], v[244:245], 0, s[98:99]
	v_mfma_f32_32x32x16_bf16 v[2:17], v[210:213], v[214:217], v[2:17]
	v_mfma_f32_32x32x16_bf16 v[18:33], v[210:213], v[218:221], v[18:33]
	s_waitcnt vmcnt(8) lgkmcnt(0)
	s_barrier
	ds_read_b128 v[206:209], v98 offset:16384
	ds_read_b128 v[210:213], v98 offset:20480
	ds_read_b128 v[214:217], v110
	ds_read_b128 v[218:221], v110 offset:8192
	v_mfma_f32_32x32x16_bf16 v[34:49], v[222:225], v[230:233], v[34:49]
	v_mfma_f32_32x32x16_bf16 v[50:65], v[222:225], v[234:237], v[50:65]
	v_mfma_f32_32x32x16_bf16 v[2:17], v[226:229], v[230:233], v[2:17]
	v_mfma_f32_32x32x16_bf16 v[18:33], v[226:229], v[234:237], v[18:33]
	ds_read_b128 v[222:225], v99 offset:16384
	ds_read_b128 v[226:229], v99 offset:20480
	ds_read_b128 v[230:233], v111
	ds_read_b128 v[234:237], v111 offset:8192
	s_waitcnt lgkmcnt(4)
	v_mfma_f32_32x32x16_bf16 v[132:147], v[206:209], v[214:217], v[132:147]
	s_add_u32 m0, s27, 0xc000
	s_nop 0
	global_load_lds_dwordx4 v[120:121], off
	v_lshl_add_u64 v[120:121], v[120:121], 0, s[98:99]
	v_mfma_f32_32x32x16_bf16 v[148:163], v[206:209], v[218:221], v[148:163]
	s_add_u32 m0, s27, 0xd000
	s_nop 0
	global_load_lds_dwordx4 v[122:123], off
	v_lshl_add_u64 v[122:123], v[122:123], 0, s[98:99]
	v_mfma_f32_32x32x16_bf16 v[164:179], v[210:213], v[214:217], v[164:179]
	v_mfma_f32_32x32x16_bf16 v[180:195], v[210:213], v[218:221], v[180:195]
	ds_read_b128 v[206:209], v100 offset:16384
	ds_read_b128 v[210:213], v100 offset:20480
	ds_read_b128 v[214:217], v128
	ds_read_b128 v[218:221], v128 offset:8192
	s_waitcnt lgkmcnt(4)
	v_mfma_f32_32x32x16_bf16 v[132:147], v[222:225], v[230:233], v[132:147]
	s_add_u32 m0, s27, 0xe000
	s_nop 0
	global_load_lds_dwordx4 v[124:125], off
	v_lshl_add_u64 v[124:125], v[124:125], 0, s[98:99]
	v_mfma_f32_32x32x16_bf16 v[148:163], v[222:225], v[234:237], v[148:163]
	v_mfma_f32_32x32x16_bf16 v[164:179], v[226:229], v[230:233], v[164:179]
	v_mfma_f32_32x32x16_bf16 v[180:195], v[226:229], v[234:237], v[180:195]
	ds_read_b128 v[222:225], v101 offset:16384
	ds_read_b128 v[226:229], v101 offset:20480
	ds_read_b128 v[230:233], v129
	ds_read_b128 v[234:237], v129 offset:8192
	s_waitcnt lgkmcnt(4)
	v_mfma_f32_32x32x16_bf16 v[132:147], v[206:209], v[214:217], v[132:147]
	s_add_u32 m0, s27, 0xf000
	s_nop 0
	global_load_lds_dwordx4 v[126:127], off
	v_lshl_add_u64 v[126:127], v[126:127], 0, s[98:99]
	v_mfma_f32_32x32x16_bf16 v[148:163], v[206:209], v[218:221], v[148:163]
	v_mfma_f32_32x32x16_bf16 v[164:179], v[210:213], v[214:217], v[164:179]
	v_mfma_f32_32x32x16_bf16 v[180:195], v[210:213], v[218:221], v[180:195]
	s_waitcnt vmcnt(4) lgkmcnt(0)
	s_barrier
	ds_read_b128 v[206:209], v98
	ds_read_b128 v[210:213], v98 offset:4096
	ds_read_b128 v[214:217], v102 offset:32768
	ds_read_b128 v[218:221], v102 offset:40960
	v_mfma_f32_32x32x16_bf16 v[132:147], v[222:225], v[230:233], v[132:147]
	v_mfma_f32_32x32x16_bf16 v[148:163], v[222:225], v[234:237], v[148:163]
	v_mfma_f32_32x32x16_bf16 v[164:179], v[226:229], v[230:233], v[164:179]
	v_mfma_f32_32x32x16_bf16 v[180:195], v[226:229], v[234:237], v[180:195]
	ds_read_b128 v[222:225], v99
	ds_read_b128 v[226:229], v99 offset:4096
	ds_read_b128 v[230:233], v103 offset:32768
	ds_read_b128 v[234:237], v103 offset:40960
	s_waitcnt lgkmcnt(4)
	v_mfma_f32_32x32x16_bf16 v[34:49], v[206:209], v[214:217], v[34:49]
	s_add_u32 m0, s27, 0x10000
	s_nop 0
	global_load_lds_dwordx4 v[246:247], off
	v_lshl_add_u64 v[246:247], v[246:247], 0, s[98:99]
	v_mfma_f32_32x32x16_bf16 v[50:65], v[206:209], v[218:221], v[50:65]
	s_add_u32 m0, s27, 0x4000
	s_nop 0
	global_load_lds_dwordx4 v[238:239], off
	v_lshl_add_u64 v[238:239], v[238:239], 0, s[98:99]
	v_mfma_f32_32x32x16_bf16 v[2:17], v[210:213], v[214:217], v[2:17]
	s_add_u32 m0, s27, 0x11000
	s_nop 0
	global_load_lds_dwordx4 v[248:249], off
	v_lshl_add_u64 v[248:249], v[248:249], 0, s[98:99]
	v_mfma_f32_32x32x16_bf16 v[18:33], v[210:213], v[218:221], v[18:33]
	ds_read_b128 v[206:209], v100
	ds_read_b128 v[210:213], v100 offset:4096
	ds_read_b128 v[214:217], v104 offset:32768
	ds_read_b128 v[218:221], v104 offset:40960
	s_waitcnt lgkmcnt(4)
	v_mfma_f32_32x32x16_bf16 v[34:49], v[222:225], v[230:233], v[34:49]
	s_add_u32 m0, s27, 0x5000
	s_nop 0
	global_load_lds_dwordx4 v[240:241], off
	v_lshl_add_u64 v[240:241], v[240:241], 0, s[98:99]
	v_mfma_f32_32x32x16_bf16 v[50:65], v[222:225], v[234:237], v[50:65]
	s_add_u32 m0, s27, 0x12000
	s_nop 0
	global_load_lds_dwordx4 v[250:251], off
	v_lshl_add_u64 v[250:251], v[250:251], 0, s[98:99]
	v_mfma_f32_32x32x16_bf16 v[2:17], v[226:229], v[230:233], v[2:17]
	s_add_u32 m0, s27, 0x6000
	s_nop 0
	global_load_lds_dwordx4 v[242:243], off
	v_lshl_add_u64 v[242:243], v[242:243], 0, s[98:99]
	v_mfma_f32_32x32x16_bf16 v[18:33], v[226:229], v[234:237], v[18:33]
	ds_read_b128 v[222:225], v101
	ds_read_b128 v[226:229], v101 offset:4096
	ds_read_b128 v[230:233], v105 offset:32768
	ds_read_b128 v[234:237], v105 offset:40960
	s_waitcnt lgkmcnt(4)
	v_mfma_f32_32x32x16_bf16 v[34:49], v[206:209], v[214:217], v[34:49]
	s_add_u32 m0, s27, 0x13000
	s_nop 0
	global_load_lds_dwordx4 v[118:119], off
	v_lshl_add_u64 v[118:119], v[118:119], 0, s[98:99]
	v_mfma_f32_32x32x16_bf16 v[50:65], v[206:209], v[218:221], v[50:65]
	s_add_u32 m0, s27, 0x7000
	s_nop 0
	global_load_lds_dwordx4 v[244:245], off
	v_lshl_add_u64 v[244:245], v[244:245], 0, s[98:99]
	v_mfma_f32_32x32x16_bf16 v[2:17], v[210:213], v[214:217], v[2:17]
	v_mfma_f32_32x32x16_bf16 v[18:33], v[210:213], v[218:221], v[18:33]
	s_waitcnt vmcnt(8) lgkmcnt(0)
	s_barrier
	ds_read_b128 v[206:209], v98
	ds_read_b128 v[210:213], v98 offset:4096
	ds_read_b128 v[214:217], v102 offset:49152
	ds_read_b128 v[218:221], v102 offset:57344
	v_mfma_f32_32x32x16_bf16 v[34:49], v[222:225], v[230:233], v[34:49]
	v_mfma_f32_32x32x16_bf16 v[50:65], v[222:225], v[234:237], v[50:65]
	v_mfma_f32_32x32x16_bf16 v[2:17], v[226:229], v[230:233], v[2:17]
	v_mfma_f32_32x32x16_bf16 v[18:33], v[226:229], v[234:237], v[18:33]
	ds_read_b128 v[222:225], v99
	ds_read_b128 v[226:229], v99 offset:4096
	ds_read_b128 v[230:233], v103 offset:49152
	ds_read_b128 v[234:237], v103 offset:57344
	s_waitcnt lgkmcnt(4)
	v_mfma_f32_32x32x16_bf16 v[132:147], v[206:209], v[214:217], v[132:147]
	s_add_u32 m0, s27, 0x8000
	s_nop 0
	global_load_lds_dwordx4 v[120:121], off
	v_lshl_add_u64 v[120:121], v[120:121], 0, s[98:99]
	v_mfma_f32_32x32x16_bf16 v[148:163], v[206:209], v[218:221], v[148:163]
	s_add_u32 m0, s27, 0x9000
	s_nop 0
	global_load_lds_dwordx4 v[122:123], off
	v_lshl_add_u64 v[122:123], v[122:123], 0, s[98:99]
	v_mfma_f32_32x32x16_bf16 v[164:179], v[210:213], v[214:217], v[164:179]
	v_mfma_f32_32x32x16_bf16 v[180:195], v[210:213], v[218:221], v[180:195]
	ds_read_b128 v[206:209], v100
	ds_read_b128 v[210:213], v100 offset:4096
	ds_read_b128 v[214:217], v104 offset:49152
	ds_read_b128 v[218:221], v104 offset:57344
	s_waitcnt lgkmcnt(4)
	v_mfma_f32_32x32x16_bf16 v[132:147], v[222:225], v[230:233], v[132:147]
	s_add_u32 m0, s27, 0xa000
	s_nop 0
	global_load_lds_dwordx4 v[124:125], off
	v_lshl_add_u64 v[124:125], v[124:125], 0, s[98:99]
	v_mfma_f32_32x32x16_bf16 v[148:163], v[222:225], v[234:237], v[148:163]
	v_mfma_f32_32x32x16_bf16 v[164:179], v[226:229], v[230:233], v[164:179]
	v_mfma_f32_32x32x16_bf16 v[180:195], v[226:229], v[234:237], v[180:195]
	ds_read_b128 v[222:225], v101
	ds_read_b128 v[226:229], v101 offset:4096
	ds_read_b128 v[230:233], v105 offset:49152
	ds_read_b128 v[234:237], v105 offset:57344
	s_waitcnt lgkmcnt(4)
	v_mfma_f32_32x32x16_bf16 v[132:147], v[206:209], v[214:217], v[132:147]
	s_add_u32 m0, s27, 0xb000
	s_nop 0
	global_load_lds_dwordx4 v[126:127], off
	v_lshl_add_u64 v[126:127], v[126:127], 0, s[98:99]
	v_mfma_f32_32x32x16_bf16 v[148:163], v[206:209], v[218:221], v[148:163]
	v_mfma_f32_32x32x16_bf16 v[164:179], v[210:213], v[214:217], v[164:179]
	v_mfma_f32_32x32x16_bf16 v[180:195], v[210:213], v[218:221], v[180:195]
	s_waitcnt vmcnt(4) lgkmcnt(0)
	s_barrier
	ds_read_b128 v[206:209], v98 offset:16384
	ds_read_b128 v[210:213], v98 offset:20480
	ds_read_b128 v[214:217], v110
	ds_read_b128 v[218:221], v110 offset:8192
	v_mfma_f32_32x32x16_bf16 v[132:147], v[222:225], v[230:233], v[132:147]
	v_mfma_f32_32x32x16_bf16 v[148:163], v[222:225], v[234:237], v[148:163]
	v_mfma_f32_32x32x16_bf16 v[164:179], v[226:229], v[230:233], v[164:179]
	v_mfma_f32_32x32x16_bf16 v[180:195], v[226:229], v[234:237], v[180:195]
	ds_read_b128 v[222:225], v99 offset:16384
	ds_read_b128 v[226:229], v99 offset:20480
	ds_read_b128 v[230:233], v111
	ds_read_b128 v[234:237], v111 offset:8192
	s_waitcnt lgkmcnt(4)
	v_mfma_f32_32x32x16_bf16 v[34:49], v[206:209], v[214:217], v[34:49]
	s_add_u32 m0, s27, 0xc000
	s_nop 0
	global_load_lds_dwordx4 v[246:247], off
	v_lshl_add_u64 v[246:247], v[246:247], 0, s[98:99]
	v_mfma_f32_32x32x16_bf16 v[50:65], v[206:209], v[218:221], v[50:65]
	s_mov_b32 m0, s27
	s_nop 0
	global_load_lds_dwordx4 v[238:239], off
	v_lshl_add_u64 v[238:239], v[238:239], 0, s[98:99]
	v_mfma_f32_32x32x16_bf16 v[2:17], v[210:213], v[214:217], v[2:17]
	s_add_u32 m0, s27, 0xd000
	s_nop 0
	global_load_lds_dwordx4 v[248:249], off
	v_lshl_add_u64 v[248:249], v[248:249], 0, s[98:99]
	v_mfma_f32_32x32x16_bf16 v[18:33], v[210:213], v[218:221], v[18:33]
	ds_read_b128 v[206:209], v100 offset:16384
	ds_read_b128 v[210:213], v100 offset:20480
	ds_read_b128 v[214:217], v128
	ds_read_b128 v[218:221], v128 offset:8192
	s_waitcnt lgkmcnt(4)
	v_mfma_f32_32x32x16_bf16 v[34:49], v[222:225], v[230:233], v[34:49]
	s_add_u32 m0, s27, 0x1000
	s_nop 0
	global_load_lds_dwordx4 v[240:241], off
	v_lshl_add_u64 v[240:241], v[240:241], 0, s[98:99]
	v_mfma_f32_32x32x16_bf16 v[50:65], v[222:225], v[234:237], v[50:65]
	s_add_u32 m0, s27, 0xe000
	s_nop 0
	global_load_lds_dwordx4 v[250:251], off
	v_lshl_add_u64 v[250:251], v[250:251], 0, s[98:99]
	v_mfma_f32_32x32x16_bf16 v[2:17], v[226:229], v[230:233], v[2:17]
	s_add_u32 m0, s27, 0x2000
	s_nop 0
	global_load_lds_dwordx4 v[242:243], off
	v_lshl_add_u64 v[242:243], v[242:243], 0, s[98:99]
	v_mfma_f32_32x32x16_bf16 v[18:33], v[226:229], v[234:237], v[18:33]
	ds_read_b128 v[222:225], v101 offset:16384
	ds_read_b128 v[226:229], v101 offset:20480
	ds_read_b128 v[230:233], v129
	ds_read_b128 v[234:237], v129 offset:8192
	s_waitcnt lgkmcnt(4)
	v_mfma_f32_32x32x16_bf16 v[34:49], v[206:209], v[214:217], v[34:49]
	s_add_u32 m0, s27, 0xf000
	s_nop 0
	global_load_lds_dwordx4 v[118:119], off
	v_lshl_add_u64 v[118:119], v[118:119], 0, s[98:99]
	v_mfma_f32_32x32x16_bf16 v[50:65], v[206:209], v[218:221], v[50:65]
	s_add_u32 m0, s27, 0x3000
	s_nop 0
	global_load_lds_dwordx4 v[244:245], off
	v_lshl_add_u64 v[244:245], v[244:245], 0, s[98:99]
	v_mfma_f32_32x32x16_bf16 v[2:17], v[210:213], v[214:217], v[2:17]
	v_mfma_f32_32x32x16_bf16 v[18:33], v[210:213], v[218:221], v[18:33]
	s_waitcnt vmcnt(8) lgkmcnt(0)
	s_barrier
	ds_read_b128 v[206:209], v98 offset:16384
	ds_read_b128 v[210:213], v98 offset:20480
	ds_read_b128 v[214:217], v102 offset:32768
	ds_read_b128 v[218:221], v102 offset:40960
	v_mfma_f32_32x32x16_bf16 v[34:49], v[222:225], v[230:233], v[34:49]
	v_mfma_f32_32x32x16_bf16 v[50:65], v[222:225], v[234:237], v[50:65]
	v_mfma_f32_32x32x16_bf16 v[2:17], v[226:229], v[230:233], v[2:17]
	v_mfma_f32_32x32x16_bf16 v[18:33], v[226:229], v[234:237], v[18:33]
	ds_read_b128 v[222:225], v99 offset:16384
	ds_read_b128 v[226:229], v99 offset:20480
	ds_read_b128 v[230:233], v103 offset:32768
	ds_read_b128 v[234:237], v103 offset:40960
	s_waitcnt lgkmcnt(4)
	v_mfma_f32_32x32x16_bf16 v[132:147], v[206:209], v[214:217], v[132:147]
	s_add_u32 m0, s27, 0x10000
	s_nop 0
	global_load_lds_dwordx4 v[120:121], off
	v_lshl_add_u64 v[120:121], v[120:121], 0, s[98:99]
	v_mfma_f32_32x32x16_bf16 v[148:163], v[206:209], v[218:221], v[148:163]
	s_add_u32 m0, s27, 0x11000
	s_nop 0
	global_load_lds_dwordx4 v[122:123], off
	v_lshl_add_u64 v[122:123], v[122:123], 0, s[98:99]
	v_mfma_f32_32x32x16_bf16 v[164:179], v[210:213], v[214:217], v[164:179]
	v_mfma_f32_32x32x16_bf16 v[180:195], v[210:213], v[218:221], v[180:195]
	ds_read_b128 v[206:209], v100 offset:16384
	ds_read_b128 v[210:213], v100 offset:20480
	ds_read_b128 v[214:217], v104 offset:32768
	ds_read_b128 v[218:221], v104 offset:40960
	s_waitcnt lgkmcnt(4)
	v_mfma_f32_32x32x16_bf16 v[132:147], v[222:225], v[230:233], v[132:147]
	s_add_u32 m0, s27, 0x12000
	s_nop 0
	global_load_lds_dwordx4 v[124:125], off
	v_lshl_add_u64 v[124:125], v[124:125], 0, s[98:99]
	v_mfma_f32_32x32x16_bf16 v[148:163], v[222:225], v[234:237], v[148:163]
	v_mfma_f32_32x32x16_bf16 v[164:179], v[226:229], v[230:233], v[164:179]
	v_mfma_f32_32x32x16_bf16 v[180:195], v[226:229], v[234:237], v[180:195]
	ds_read_b128 v[222:225], v101 offset:16384
	ds_read_b128 v[226:229], v101 offset:20480
	ds_read_b128 v[230:233], v105 offset:32768
	ds_read_b128 v[234:237], v105 offset:40960
	s_waitcnt lgkmcnt(4)
	v_mfma_f32_32x32x16_bf16 v[132:147], v[206:209], v[214:217], v[132:147]
	s_add_u32 m0, s27, 0x13000
	s_nop 0
	global_load_lds_dwordx4 v[126:127], off
	v_lshl_add_u64 v[126:127], v[126:127], 0, s[98:99]
	v_mfma_f32_32x32x16_bf16 v[148:163], v[206:209], v[218:221], v[148:163]
	v_mfma_f32_32x32x16_bf16 v[164:179], v[210:213], v[214:217], v[164:179]
	v_mfma_f32_32x32x16_bf16 v[180:195], v[210:213], v[218:221], v[180:195]
	s_waitcnt vmcnt(4) lgkmcnt(0)
	s_barrier
	ds_read_b128 v[206:209], v98
	ds_read_b128 v[210:213], v98 offset:4096
	ds_read_b128 v[214:217], v102 offset:49152
	ds_read_b128 v[218:221], v102 offset:57344
	v_mfma_f32_32x32x16_bf16 v[132:147], v[222:225], v[230:233], v[132:147]
	v_mfma_f32_32x32x16_bf16 v[148:163], v[222:225], v[234:237], v[148:163]
	v_mfma_f32_32x32x16_bf16 v[164:179], v[226:229], v[230:233], v[164:179]
	v_mfma_f32_32x32x16_bf16 v[180:195], v[226:229], v[234:237], v[180:195]
	ds_read_b128 v[222:225], v99
	ds_read_b128 v[226:229], v99 offset:4096
	ds_read_b128 v[230:233], v103 offset:49152
	ds_read_b128 v[234:237], v103 offset:57344
	s_waitcnt lgkmcnt(4)
	v_mfma_f32_32x32x16_bf16 v[34:49], v[206:209], v[214:217], v[34:49]
	s_add_u32 m0, s27, 0x8000
	s_nop 0
	global_load_lds_dwordx4 v[246:247], off
	v_lshl_add_u64 v[246:247], v[246:247], 0, s[98:99]
	v_mfma_f32_32x32x16_bf16 v[50:65], v[206:209], v[218:221], v[50:65]
	s_add_u32 m0, s27, 0x4000
	s_nop 0
	global_load_lds_dwordx4 v[238:239], off
	v_lshl_add_u64 v[238:239], v[238:239], 0, s[98:99]
	v_mfma_f32_32x32x16_bf16 v[2:17], v[210:213], v[214:217], v[2:17]
	s_add_u32 m0, s27, 0x9000
	s_nop 0
	global_load_lds_dwordx4 v[248:249], off
	v_lshl_add_u64 v[248:249], v[248:249], 0, s[98:99]
	v_mfma_f32_32x32x16_bf16 v[18:33], v[210:213], v[218:221], v[18:33]
	ds_read_b128 v[206:209], v100
	ds_read_b128 v[210:213], v100 offset:4096
	ds_read_b128 v[214:217], v104 offset:49152
	ds_read_b128 v[218:221], v104 offset:57344
	s_waitcnt lgkmcnt(4)
	v_mfma_f32_32x32x16_bf16 v[34:49], v[222:225], v[230:233], v[34:49]
	s_add_u32 m0, s27, 0x5000
	s_nop 0
	global_load_lds_dwordx4 v[240:241], off
	v_lshl_add_u64 v[240:241], v[240:241], 0, s[98:99]
	v_mfma_f32_32x32x16_bf16 v[50:65], v[222:225], v[234:237], v[50:65]
	s_add_u32 m0, s27, 0xa000
	s_nop 0
	global_load_lds_dwordx4 v[250:251], off
	v_lshl_add_u64 v[250:251], v[250:251], 0, s[98:99]
	v_mfma_f32_32x32x16_bf16 v[2:17], v[226:229], v[230:233], v[2:17]
	s_add_u32 m0, s27, 0x6000
	s_nop 0
	global_load_lds_dwordx4 v[242:243], off
	v_lshl_add_u64 v[242:243], v[242:243], 0, s[98:99]
	v_mfma_f32_32x32x16_bf16 v[18:33], v[226:229], v[234:237], v[18:33]
	ds_read_b128 v[222:225], v101
	ds_read_b128 v[226:229], v101 offset:4096
	ds_read_b128 v[230:233], v105 offset:49152
	ds_read_b128 v[234:237], v105 offset:57344
	s_waitcnt lgkmcnt(4)
	v_mfma_f32_32x32x16_bf16 v[34:49], v[206:209], v[214:217], v[34:49]
	s_add_u32 m0, s27, 0xb000
	s_nop 0
	global_load_lds_dwordx4 v[118:119], off
	v_lshl_add_u64 v[118:119], v[118:119], 0, s[98:99]
	v_mfma_f32_32x32x16_bf16 v[50:65], v[206:209], v[218:221], v[50:65]
	s_add_u32 m0, s27, 0x7000
	s_nop 0
	global_load_lds_dwordx4 v[244:245], off
	v_lshl_add_u64 v[244:245], v[244:245], 0, s[98:99]
	v_mfma_f32_32x32x16_bf16 v[2:17], v[210:213], v[214:217], v[2:17]
	v_mfma_f32_32x32x16_bf16 v[18:33], v[210:213], v[218:221], v[18:33]
	s_waitcnt vmcnt(8) lgkmcnt(0)
	s_barrier
	ds_read_b128 v[206:209], v98
	ds_read_b128 v[210:213], v98 offset:4096
	ds_read_b128 v[214:217], v110
	ds_read_b128 v[218:221], v110 offset:8192
	v_mfma_f32_32x32x16_bf16 v[34:49], v[222:225], v[230:233], v[34:49]
	v_mfma_f32_32x32x16_bf16 v[50:65], v[222:225], v[234:237], v[50:65]
	v_mfma_f32_32x32x16_bf16 v[2:17], v[226:229], v[230:233], v[2:17]
	v_mfma_f32_32x32x16_bf16 v[18:33], v[226:229], v[234:237], v[18:33]
	ds_read_b128 v[222:225], v99
	ds_read_b128 v[226:229], v99 offset:4096
	ds_read_b128 v[230:233], v111
	ds_read_b128 v[234:237], v111 offset:8192
	s_waitcnt lgkmcnt(4)
	v_mfma_f32_32x32x16_bf16 v[132:147], v[206:209], v[214:217], v[132:147]
	s_add_u32 m0, s27, 0xc000
	s_nop 0
	global_load_lds_dwordx4 v[120:121], off
	v_lshl_add_u64 v[120:121], v[120:121], 0, s[98:99]
	v_mfma_f32_32x32x16_bf16 v[148:163], v[206:209], v[218:221], v[148:163]
	s_add_u32 m0, s27, 0xd000
	s_nop 0
	global_load_lds_dwordx4 v[122:123], off
	v_lshl_add_u64 v[122:123], v[122:123], 0, s[98:99]
	v_mfma_f32_32x32x16_bf16 v[164:179], v[210:213], v[214:217], v[164:179]
	v_mfma_f32_32x32x16_bf16 v[180:195], v[210:213], v[218:221], v[180:195]
	ds_read_b128 v[206:209], v100
	ds_read_b128 v[210:213], v100 offset:4096
	ds_read_b128 v[214:217], v128
	ds_read_b128 v[218:221], v128 offset:8192
	s_waitcnt lgkmcnt(4)
	v_mfma_f32_32x32x16_bf16 v[132:147], v[222:225], v[230:233], v[132:147]
	s_add_u32 m0, s27, 0xe000
	s_nop 0
	global_load_lds_dwordx4 v[124:125], off
	v_lshl_add_u64 v[124:125], v[124:125], 0, s[98:99]
	v_mfma_f32_32x32x16_bf16 v[148:163], v[222:225], v[234:237], v[148:163]
	v_mfma_f32_32x32x16_bf16 v[164:179], v[226:229], v[230:233], v[164:179]
	v_mfma_f32_32x32x16_bf16 v[180:195], v[226:229], v[234:237], v[180:195]
	ds_read_b128 v[222:225], v101
	ds_read_b128 v[226:229], v101 offset:4096
	ds_read_b128 v[230:233], v129
	ds_read_b128 v[234:237], v129 offset:8192
	s_waitcnt lgkmcnt(4)
	v_mfma_f32_32x32x16_bf16 v[132:147], v[206:209], v[214:217], v[132:147]
	s_add_u32 m0, s27, 0xf000
	s_nop 0
	global_load_lds_dwordx4 v[126:127], off
	v_lshl_add_u64 v[126:127], v[126:127], 0, s[98:99]
	v_mfma_f32_32x32x16_bf16 v[148:163], v[206:209], v[218:221], v[148:163]
	v_mfma_f32_32x32x16_bf16 v[164:179], v[210:213], v[214:217], v[164:179]
	v_mfma_f32_32x32x16_bf16 v[180:195], v[210:213], v[218:221], v[180:195]
	s_waitcnt vmcnt(4) lgkmcnt(0)
	s_barrier
	ds_read_b128 v[206:209], v98 offset:16384
	ds_read_b128 v[210:213], v98 offset:20480
	ds_read_b128 v[214:217], v102 offset:32768
	ds_read_b128 v[218:221], v102 offset:40960
	v_mfma_f32_32x32x16_bf16 v[132:147], v[222:225], v[230:233], v[132:147]
	v_mfma_f32_32x32x16_bf16 v[148:163], v[222:225], v[234:237], v[148:163]
	v_mfma_f32_32x32x16_bf16 v[164:179], v[226:229], v[230:233], v[164:179]
	v_mfma_f32_32x32x16_bf16 v[180:195], v[226:229], v[234:237], v[180:195]
	ds_read_b128 v[222:225], v99 offset:16384
	ds_read_b128 v[226:229], v99 offset:20480
	ds_read_b128 v[230:233], v103 offset:32768
	ds_read_b128 v[234:237], v103 offset:40960
	s_waitcnt lgkmcnt(4)
	v_mfma_f32_32x32x16_bf16 v[34:49], v[206:209], v[214:217], v[34:49]
	s_add_u32 m0, s27, 0x10000
	s_nop 0
	global_load_lds_dwordx4 v[246:247], off
	v_lshl_add_u64 v[246:247], v[246:247], 0, s[98:99]
	v_mfma_f32_32x32x16_bf16 v[50:65], v[206:209], v[218:221], v[50:65]
	s_mov_b32 m0, s27
	s_nop 0
	global_load_lds_dwordx4 v[238:239], off
	v_lshl_add_u64 v[238:239], v[238:239], 0, s[98:99]
	v_mfma_f32_32x32x16_bf16 v[2:17], v[210:213], v[214:217], v[2:17]
	s_add_u32 m0, s27, 0x11000
	s_nop 0
	global_load_lds_dwordx4 v[248:249], off
	v_lshl_add_u64 v[248:249], v[248:249], 0, s[98:99]
	v_mfma_f32_32x32x16_bf16 v[18:33], v[210:213], v[218:221], v[18:33]
	ds_read_b128 v[206:209], v100 offset:16384
	ds_read_b128 v[210:213], v100 offset:20480
	ds_read_b128 v[214:217], v104 offset:32768
	ds_read_b128 v[218:221], v104 offset:40960
	s_waitcnt lgkmcnt(4)
	v_mfma_f32_32x32x16_bf16 v[34:49], v[222:225], v[230:233], v[34:49]
	s_add_u32 m0, s27, 0x1000
	s_nop 0
	global_load_lds_dwordx4 v[240:241], off
	v_lshl_add_u64 v[240:241], v[240:241], 0, s[98:99]
	v_mfma_f32_32x32x16_bf16 v[50:65], v[222:225], v[234:237], v[50:65]
	s_add_u32 m0, s27, 0x12000
	s_nop 0
	global_load_lds_dwordx4 v[250:251], off
	v_lshl_add_u64 v[250:251], v[250:251], 0, s[98:99]
	v_mfma_f32_32x32x16_bf16 v[2:17], v[226:229], v[230:233], v[2:17]
	s_add_u32 m0, s27, 0x2000
	s_nop 0
	global_load_lds_dwordx4 v[242:243], off
	v_lshl_add_u64 v[242:243], v[242:243], 0, s[98:99]
	v_mfma_f32_32x32x16_bf16 v[18:33], v[226:229], v[234:237], v[18:33]
	ds_read_b128 v[222:225], v101 offset:16384
	ds_read_b128 v[226:229], v101 offset:20480
	ds_read_b128 v[230:233], v105 offset:32768
	ds_read_b128 v[234:237], v105 offset:40960
	s_waitcnt lgkmcnt(4)
	v_mfma_f32_32x32x16_bf16 v[34:49], v[206:209], v[214:217], v[34:49]
	s_add_u32 m0, s27, 0x13000
	s_nop 0
	global_load_lds_dwordx4 v[118:119], off
	v_lshl_add_u64 v[118:119], v[118:119], 0, s[98:99]
	v_mfma_f32_32x32x16_bf16 v[50:65], v[206:209], v[218:221], v[50:65]
	s_add_u32 m0, s27, 0x3000
	s_nop 0
	global_load_lds_dwordx4 v[244:245], off
	v_lshl_add_u64 v[244:245], v[244:245], 0, s[98:99]
	v_mfma_f32_32x32x16_bf16 v[2:17], v[210:213], v[214:217], v[2:17]
	v_mfma_f32_32x32x16_bf16 v[18:33], v[210:213], v[218:221], v[18:33]
	s_waitcnt vmcnt(8) lgkmcnt(0)
	s_barrier
	ds_read_b128 v[206:209], v98 offset:16384
	ds_read_b128 v[210:213], v98 offset:20480
	ds_read_b128 v[214:217], v102 offset:49152
	ds_read_b128 v[218:221], v102 offset:57344
	v_mfma_f32_32x32x16_bf16 v[34:49], v[222:225], v[230:233], v[34:49]
	v_mfma_f32_32x32x16_bf16 v[50:65], v[222:225], v[234:237], v[50:65]
	v_mfma_f32_32x32x16_bf16 v[2:17], v[226:229], v[230:233], v[2:17]
	v_mfma_f32_32x32x16_bf16 v[18:33], v[226:229], v[234:237], v[18:33]
	ds_read_b128 v[222:225], v99 offset:16384
	ds_read_b128 v[226:229], v99 offset:20480
	ds_read_b128 v[230:233], v103 offset:49152
	ds_read_b128 v[234:237], v103 offset:57344
	s_waitcnt lgkmcnt(4)
	v_mfma_f32_32x32x16_bf16 v[132:147], v[206:209], v[214:217], v[132:147]
	s_add_u32 m0, s27, 0x8000
	s_nop 0
	global_load_lds_dwordx4 v[120:121], off
	v_lshl_add_u64 v[120:121], v[120:121], 0, s[98:99]
	v_mfma_f32_32x32x16_bf16 v[148:163], v[206:209], v[218:221], v[148:163]
	s_add_u32 m0, s27, 0x9000
	s_nop 0
	global_load_lds_dwordx4 v[122:123], off
	v_lshl_add_u64 v[122:123], v[122:123], 0, s[98:99]
	v_mfma_f32_32x32x16_bf16 v[164:179], v[210:213], v[214:217], v[164:179]
	v_mfma_f32_32x32x16_bf16 v[180:195], v[210:213], v[218:221], v[180:195]
	ds_read_b128 v[206:209], v100 offset:16384
	ds_read_b128 v[210:213], v100 offset:20480
	ds_read_b128 v[214:217], v104 offset:49152
	ds_read_b128 v[218:221], v104 offset:57344
	s_waitcnt lgkmcnt(4)
	v_mfma_f32_32x32x16_bf16 v[132:147], v[222:225], v[230:233], v[132:147]
	s_add_u32 m0, s27, 0xa000
	s_nop 0
	global_load_lds_dwordx4 v[124:125], off
	v_lshl_add_u64 v[124:125], v[124:125], 0, s[98:99]
	v_mfma_f32_32x32x16_bf16 v[148:163], v[222:225], v[234:237], v[148:163]
	v_mfma_f32_32x32x16_bf16 v[164:179], v[226:229], v[230:233], v[164:179]
	v_mfma_f32_32x32x16_bf16 v[180:195], v[226:229], v[234:237], v[180:195]
	ds_read_b128 v[222:225], v101 offset:16384
	ds_read_b128 v[226:229], v101 offset:20480
	ds_read_b128 v[230:233], v105 offset:49152
	ds_read_b128 v[234:237], v105 offset:57344
	s_waitcnt lgkmcnt(4)
	v_mfma_f32_32x32x16_bf16 v[132:147], v[206:209], v[214:217], v[132:147]
	s_add_u32 m0, s27, 0xb000
	s_nop 0
	global_load_lds_dwordx4 v[126:127], off
	v_lshl_add_u64 v[126:127], v[126:127], 0, s[98:99]
	v_mfma_f32_32x32x16_bf16 v[148:163], v[206:209], v[218:221], v[148:163]
	v_mfma_f32_32x32x16_bf16 v[164:179], v[210:213], v[214:217], v[164:179]
	v_mfma_f32_32x32x16_bf16 v[180:195], v[210:213], v[218:221], v[180:195]
	s_waitcnt vmcnt(4) lgkmcnt(0)
	s_barrier
	ds_read_b128 v[206:209], v98
	ds_read_b128 v[210:213], v98 offset:4096
	ds_read_b128 v[214:217], v110
	ds_read_b128 v[218:221], v110 offset:8192
	v_mfma_f32_32x32x16_bf16 v[132:147], v[222:225], v[230:233], v[132:147]
	v_mfma_f32_32x32x16_bf16 v[148:163], v[222:225], v[234:237], v[148:163]
	v_mfma_f32_32x32x16_bf16 v[164:179], v[226:229], v[230:233], v[164:179]
	v_mfma_f32_32x32x16_bf16 v[180:195], v[226:229], v[234:237], v[180:195]
	ds_read_b128 v[222:225], v99
	ds_read_b128 v[226:229], v99 offset:4096
	ds_read_b128 v[230:233], v111
	ds_read_b128 v[234:237], v111 offset:8192
	s_waitcnt lgkmcnt(4)
	v_mfma_f32_32x32x16_bf16 v[34:49], v[206:209], v[214:217], v[34:49]
	s_add_u32 m0, s27, 0xc000
	s_nop 0
	global_load_lds_dwordx4 v[246:247], off
	v_lshl_add_u64 v[246:247], v[246:247], 0, s[98:99]
	v_mfma_f32_32x32x16_bf16 v[50:65], v[206:209], v[218:221], v[50:65]
	s_add_u32 m0, s27, 0x4000
	s_nop 0
	global_load_lds_dwordx4 v[238:239], off
	v_lshl_add_u64 v[238:239], v[238:239], 0, s[98:99]
	v_mfma_f32_32x32x16_bf16 v[2:17], v[210:213], v[214:217], v[2:17]
	s_add_u32 m0, s27, 0xd000
	s_nop 0
	global_load_lds_dwordx4 v[248:249], off
	v_lshl_add_u64 v[248:249], v[248:249], 0, s[98:99]
	v_mfma_f32_32x32x16_bf16 v[18:33], v[210:213], v[218:221], v[18:33]
	ds_read_b128 v[206:209], v100
	ds_read_b128 v[210:213], v100 offset:4096
	ds_read_b128 v[214:217], v128
	ds_read_b128 v[218:221], v128 offset:8192
	s_waitcnt lgkmcnt(4)
	v_mfma_f32_32x32x16_bf16 v[34:49], v[222:225], v[230:233], v[34:49]
	s_add_u32 m0, s27, 0x5000
	s_nop 0
	global_load_lds_dwordx4 v[240:241], off
	v_lshl_add_u64 v[240:241], v[240:241], 0, s[98:99]
	v_mfma_f32_32x32x16_bf16 v[50:65], v[222:225], v[234:237], v[50:65]
	s_add_u32 m0, s27, 0xe000
	s_nop 0
	global_load_lds_dwordx4 v[250:251], off
	v_lshl_add_u64 v[250:251], v[250:251], 0, s[98:99]
	v_mfma_f32_32x32x16_bf16 v[2:17], v[226:229], v[230:233], v[2:17]
	s_add_u32 m0, s27, 0x6000
	s_nop 0
	global_load_lds_dwordx4 v[242:243], off
	v_lshl_add_u64 v[242:243], v[242:243], 0, s[98:99]
	v_mfma_f32_32x32x16_bf16 v[18:33], v[226:229], v[234:237], v[18:33]
	ds_read_b128 v[222:225], v101
	ds_read_b128 v[226:229], v101 offset:4096
	ds_read_b128 v[230:233], v129
	ds_read_b128 v[234:237], v129 offset:8192
	s_waitcnt lgkmcnt(4)
	v_mfma_f32_32x32x16_bf16 v[34:49], v[206:209], v[214:217], v[34:49]
	s_add_u32 m0, s27, 0xf000
	s_nop 0
	global_load_lds_dwordx4 v[118:119], off
	v_lshl_add_u64 v[118:119], v[118:119], 0, s[98:99]
	v_mfma_f32_32x32x16_bf16 v[50:65], v[206:209], v[218:221], v[50:65]
	s_add_u32 m0, s27, 0x7000
	s_nop 0
	global_load_lds_dwordx4 v[244:245], off
	v_lshl_add_u64 v[244:245], v[244:245], 0, s[98:99]
	v_mfma_f32_32x32x16_bf16 v[2:17], v[210:213], v[214:217], v[2:17]
	v_mfma_f32_32x32x16_bf16 v[18:33], v[210:213], v[218:221], v[18:33]
	s_waitcnt vmcnt(8) lgkmcnt(0)
	s_barrier
	ds_read_b128 v[206:209], v98
	ds_read_b128 v[210:213], v98 offset:4096
	ds_read_b128 v[214:217], v102 offset:32768
	ds_read_b128 v[218:221], v102 offset:40960
	v_mfma_f32_32x32x16_bf16 v[34:49], v[222:225], v[230:233], v[34:49]
	v_mfma_f32_32x32x16_bf16 v[50:65], v[222:225], v[234:237], v[50:65]
	v_mfma_f32_32x32x16_bf16 v[2:17], v[226:229], v[230:233], v[2:17]
	v_mfma_f32_32x32x16_bf16 v[18:33], v[226:229], v[234:237], v[18:33]
	ds_read_b128 v[222:225], v99
	ds_read_b128 v[226:229], v99 offset:4096
	ds_read_b128 v[230:233], v103 offset:32768
	ds_read_b128 v[234:237], v103 offset:40960
	s_waitcnt lgkmcnt(4)
	v_mfma_f32_32x32x16_bf16 v[132:147], v[206:209], v[214:217], v[132:147]
	s_add_u32 m0, s27, 0x10000
	s_nop 0
	global_load_lds_dwordx4 v[120:121], off
	v_lshl_add_u64 v[120:121], v[120:121], 0, s[98:99]
	v_mfma_f32_32x32x16_bf16 v[148:163], v[206:209], v[218:221], v[148:163]
	s_add_u32 m0, s27, 0x11000
	s_nop 0
	global_load_lds_dwordx4 v[122:123], off
	v_lshl_add_u64 v[122:123], v[122:123], 0, s[98:99]
	v_mfma_f32_32x32x16_bf16 v[164:179], v[210:213], v[214:217], v[164:179]
	v_mfma_f32_32x32x16_bf16 v[180:195], v[210:213], v[218:221], v[180:195]
	ds_read_b128 v[206:209], v100
	ds_read_b128 v[210:213], v100 offset:4096
	ds_read_b128 v[214:217], v104 offset:32768
	ds_read_b128 v[218:221], v104 offset:40960
	s_waitcnt lgkmcnt(4)
	v_mfma_f32_32x32x16_bf16 v[132:147], v[222:225], v[230:233], v[132:147]
	s_add_u32 m0, s27, 0x12000
	s_nop 0
	global_load_lds_dwordx4 v[124:125], off
	v_lshl_add_u64 v[124:125], v[124:125], 0, s[98:99]
	v_mfma_f32_32x32x16_bf16 v[148:163], v[222:225], v[234:237], v[148:163]
	v_mfma_f32_32x32x16_bf16 v[164:179], v[226:229], v[230:233], v[164:179]
	v_mfma_f32_32x32x16_bf16 v[180:195], v[226:229], v[234:237], v[180:195]
	ds_read_b128 v[222:225], v101
	ds_read_b128 v[226:229], v101 offset:4096
	ds_read_b128 v[230:233], v105 offset:32768
	ds_read_b128 v[234:237], v105 offset:40960
	s_waitcnt lgkmcnt(4)
	v_mfma_f32_32x32x16_bf16 v[132:147], v[206:209], v[214:217], v[132:147]
	s_add_u32 m0, s27, 0x13000
	s_nop 0
	global_load_lds_dwordx4 v[126:127], off
	v_lshl_add_u64 v[126:127], v[126:127], 0, s[98:99]
	v_mfma_f32_32x32x16_bf16 v[148:163], v[206:209], v[218:221], v[148:163]
	v_mfma_f32_32x32x16_bf16 v[164:179], v[210:213], v[214:217], v[164:179]
	v_mfma_f32_32x32x16_bf16 v[180:195], v[210:213], v[218:221], v[180:195]
	s_waitcnt vmcnt(4) lgkmcnt(0)
	s_barrier
	ds_read_b128 v[206:209], v98 offset:16384
	ds_read_b128 v[210:213], v98 offset:20480
	ds_read_b128 v[214:217], v102 offset:49152
	ds_read_b128 v[218:221], v102 offset:57344
	v_mfma_f32_32x32x16_bf16 v[132:147], v[222:225], v[230:233], v[132:147]
	v_mfma_f32_32x32x16_bf16 v[148:163], v[222:225], v[234:237], v[148:163]
	v_mfma_f32_32x32x16_bf16 v[164:179], v[226:229], v[230:233], v[164:179]
	v_mfma_f32_32x32x16_bf16 v[180:195], v[226:229], v[234:237], v[180:195]
	ds_read_b128 v[222:225], v99 offset:16384
	ds_read_b128 v[226:229], v99 offset:20480
	ds_read_b128 v[230:233], v103 offset:49152
	ds_read_b128 v[234:237], v103 offset:57344
	s_waitcnt lgkmcnt(4)
	v_mfma_f32_32x32x16_bf16 v[34:49], v[206:209], v[214:217], v[34:49]
	s_add_u32 m0, s27, 0x8000
	s_nop 0
	global_load_lds_dwordx4 v[246:247], off
	v_lshl_add_u64 v[246:247], v[246:247], 0, s[98:99]
	v_mfma_f32_32x32x16_bf16 v[50:65], v[206:209], v[218:221], v[50:65]
	s_mov_b32 m0, s27
	s_nop 0
	global_load_lds_dwordx4 v[238:239], off
	v_lshl_add_u64 v[238:239], v[238:239], 0, s[98:99]
	v_mfma_f32_32x32x16_bf16 v[2:17], v[210:213], v[214:217], v[2:17]
	s_add_u32 m0, s27, 0x9000
	s_nop 0
	global_load_lds_dwordx4 v[248:249], off
	v_lshl_add_u64 v[248:249], v[248:249], 0, s[98:99]
	v_mfma_f32_32x32x16_bf16 v[18:33], v[210:213], v[218:221], v[18:33]
	ds_read_b128 v[206:209], v100 offset:16384
	ds_read_b128 v[210:213], v100 offset:20480
	ds_read_b128 v[214:217], v104 offset:49152
	ds_read_b128 v[218:221], v104 offset:57344
	s_waitcnt lgkmcnt(4)
	v_mfma_f32_32x32x16_bf16 v[34:49], v[222:225], v[230:233], v[34:49]
	s_add_u32 m0, s27, 0x1000
	s_nop 0
	global_load_lds_dwordx4 v[240:241], off
	v_lshl_add_u64 v[240:241], v[240:241], 0, s[98:99]
	v_mfma_f32_32x32x16_bf16 v[50:65], v[222:225], v[234:237], v[50:65]
	s_add_u32 m0, s27, 0xa000
	s_nop 0
	global_load_lds_dwordx4 v[250:251], off
	v_lshl_add_u64 v[250:251], v[250:251], 0, s[98:99]
	v_mfma_f32_32x32x16_bf16 v[2:17], v[226:229], v[230:233], v[2:17]
	s_add_u32 m0, s27, 0x2000
	s_nop 0
	global_load_lds_dwordx4 v[242:243], off
	v_lshl_add_u64 v[242:243], v[242:243], 0, s[98:99]
	v_mfma_f32_32x32x16_bf16 v[18:33], v[226:229], v[234:237], v[18:33]
	ds_read_b128 v[222:225], v101 offset:16384
	ds_read_b128 v[226:229], v101 offset:20480
	ds_read_b128 v[230:233], v105 offset:49152
	ds_read_b128 v[234:237], v105 offset:57344
	s_waitcnt lgkmcnt(4)
	v_mfma_f32_32x32x16_bf16 v[34:49], v[206:209], v[214:217], v[34:49]
	s_add_u32 m0, s27, 0xb000
	s_nop 0
	global_load_lds_dwordx4 v[118:119], off
	v_lshl_add_u64 v[118:119], v[118:119], 0, s[98:99]
	v_mfma_f32_32x32x16_bf16 v[50:65], v[206:209], v[218:221], v[50:65]
	s_add_u32 m0, s27, 0x3000
	s_nop 0
	global_load_lds_dwordx4 v[244:245], off
	v_lshl_add_u64 v[244:245], v[244:245], 0, s[98:99]
	v_mfma_f32_32x32x16_bf16 v[2:17], v[210:213], v[214:217], v[2:17]
	v_mfma_f32_32x32x16_bf16 v[18:33], v[210:213], v[218:221], v[18:33]
	s_waitcnt vmcnt(8) lgkmcnt(0)
	s_barrier
	ds_read_b128 v[206:209], v98 offset:16384
	ds_read_b128 v[210:213], v98 offset:20480
	ds_read_b128 v[214:217], v110
	ds_read_b128 v[218:221], v110 offset:8192
	v_mfma_f32_32x32x16_bf16 v[34:49], v[222:225], v[230:233], v[34:49]
	v_mfma_f32_32x32x16_bf16 v[50:65], v[222:225], v[234:237], v[50:65]
	v_mfma_f32_32x32x16_bf16 v[2:17], v[226:229], v[230:233], v[2:17]
	v_mfma_f32_32x32x16_bf16 v[18:33], v[226:229], v[234:237], v[18:33]
	ds_read_b128 v[222:225], v99 offset:16384
	ds_read_b128 v[226:229], v99 offset:20480
	ds_read_b128 v[230:233], v111
	ds_read_b128 v[234:237], v111 offset:8192
	s_waitcnt lgkmcnt(4)
	v_mfma_f32_32x32x16_bf16 v[132:147], v[206:209], v[214:217], v[132:147]
	s_add_u32 m0, s27, 0xc000
	s_nop 0
	global_load_lds_dwordx4 v[120:121], off
	v_lshl_add_u64 v[120:121], v[120:121], 0, s[98:99]
	v_mfma_f32_32x32x16_bf16 v[148:163], v[206:209], v[218:221], v[148:163]
	s_add_u32 m0, s27, 0xd000
	s_nop 0
	global_load_lds_dwordx4 v[122:123], off
	v_lshl_add_u64 v[122:123], v[122:123], 0, s[98:99]
	v_mfma_f32_32x32x16_bf16 v[164:179], v[210:213], v[214:217], v[164:179]
	v_mfma_f32_32x32x16_bf16 v[180:195], v[210:213], v[218:221], v[180:195]
	ds_read_b128 v[206:209], v100 offset:16384
	ds_read_b128 v[210:213], v100 offset:20480
	ds_read_b128 v[214:217], v128
	ds_read_b128 v[218:221], v128 offset:8192
	s_waitcnt lgkmcnt(4)
	v_mfma_f32_32x32x16_bf16 v[132:147], v[222:225], v[230:233], v[132:147]
	s_add_u32 m0, s27, 0xe000
	s_nop 0
	global_load_lds_dwordx4 v[124:125], off
	v_lshl_add_u64 v[124:125], v[124:125], 0, s[98:99]
	v_mfma_f32_32x32x16_bf16 v[148:163], v[222:225], v[234:237], v[148:163]
	v_mfma_f32_32x32x16_bf16 v[164:179], v[226:229], v[230:233], v[164:179]
	v_mfma_f32_32x32x16_bf16 v[180:195], v[226:229], v[234:237], v[180:195]
	ds_read_b128 v[222:225], v101 offset:16384
	ds_read_b128 v[226:229], v101 offset:20480
	ds_read_b128 v[230:233], v129
	ds_read_b128 v[234:237], v129 offset:8192
	s_waitcnt lgkmcnt(4)
	v_mfma_f32_32x32x16_bf16 v[132:147], v[206:209], v[214:217], v[132:147]
	s_add_u32 m0, s27, 0xf000
	s_nop 0
	global_load_lds_dwordx4 v[126:127], off
	v_lshl_add_u64 v[126:127], v[126:127], 0, s[98:99]
	v_mfma_f32_32x32x16_bf16 v[148:163], v[206:209], v[218:221], v[148:163]
	v_mfma_f32_32x32x16_bf16 v[164:179], v[210:213], v[214:217], v[164:179]
	v_mfma_f32_32x32x16_bf16 v[180:195], v[210:213], v[218:221], v[180:195]
	s_waitcnt vmcnt(4) lgkmcnt(0)
	s_barrier
	ds_read_b128 v[206:209], v98
	ds_read_b128 v[210:213], v98 offset:4096
	ds_read_b128 v[214:217], v102 offset:32768
	ds_read_b128 v[218:221], v102 offset:40960
	v_mfma_f32_32x32x16_bf16 v[132:147], v[222:225], v[230:233], v[132:147]
	v_mfma_f32_32x32x16_bf16 v[148:163], v[222:225], v[234:237], v[148:163]
	v_mfma_f32_32x32x16_bf16 v[164:179], v[226:229], v[230:233], v[164:179]
	v_mfma_f32_32x32x16_bf16 v[180:195], v[226:229], v[234:237], v[180:195]
	ds_read_b128 v[222:225], v99
	ds_read_b128 v[226:229], v99 offset:4096
	ds_read_b128 v[230:233], v103 offset:32768
	ds_read_b128 v[234:237], v103 offset:40960
	s_waitcnt lgkmcnt(4)
	v_mfma_f32_32x32x16_bf16 v[34:49], v[206:209], v[214:217], v[34:49]
	s_add_u32 m0, s27, 0x10000
	s_nop 0
	global_load_lds_dwordx4 v[246:247], off
	v_lshl_add_u64 v[246:247], v[246:247], 0, s[98:99]
	v_mfma_f32_32x32x16_bf16 v[50:65], v[206:209], v[218:221], v[50:65]
	s_add_u32 m0, s27, 0x4000
	s_nop 0
	global_load_lds_dwordx4 v[238:239], off
	v_lshl_add_u64 v[238:239], v[238:239], 0, s[98:99]
	v_mfma_f32_32x32x16_bf16 v[2:17], v[210:213], v[214:217], v[2:17]
	s_add_u32 m0, s27, 0x11000
	s_nop 0
	global_load_lds_dwordx4 v[248:249], off
	v_lshl_add_u64 v[248:249], v[248:249], 0, s[98:99]
	v_mfma_f32_32x32x16_bf16 v[18:33], v[210:213], v[218:221], v[18:33]
	ds_read_b128 v[206:209], v100
	ds_read_b128 v[210:213], v100 offset:4096
	ds_read_b128 v[214:217], v104 offset:32768
	ds_read_b128 v[218:221], v104 offset:40960
	s_waitcnt lgkmcnt(4)
	v_mfma_f32_32x32x16_bf16 v[34:49], v[222:225], v[230:233], v[34:49]
	s_add_u32 m0, s27, 0x5000
	s_nop 0
	global_load_lds_dwordx4 v[240:241], off
	v_lshl_add_u64 v[240:241], v[240:241], 0, s[98:99]
	v_mfma_f32_32x32x16_bf16 v[50:65], v[222:225], v[234:237], v[50:65]
	s_add_u32 m0, s27, 0x12000
	s_nop 0
	global_load_lds_dwordx4 v[250:251], off
	v_lshl_add_u64 v[250:251], v[250:251], 0, s[98:99]
	v_mfma_f32_32x32x16_bf16 v[2:17], v[226:229], v[230:233], v[2:17]
	s_add_u32 m0, s27, 0x6000
	s_nop 0
	global_load_lds_dwordx4 v[242:243], off
	v_lshl_add_u64 v[242:243], v[242:243], 0, s[98:99]
	v_mfma_f32_32x32x16_bf16 v[18:33], v[226:229], v[234:237], v[18:33]
	ds_read_b128 v[222:225], v101
	ds_read_b128 v[226:229], v101 offset:4096
	ds_read_b128 v[230:233], v105 offset:32768
	ds_read_b128 v[234:237], v105 offset:40960
	s_waitcnt lgkmcnt(4)
	v_mfma_f32_32x32x16_bf16 v[34:49], v[206:209], v[214:217], v[34:49]
	s_add_u32 m0, s27, 0x13000
	s_nop 0
	global_load_lds_dwordx4 v[118:119], off
	v_lshl_add_u64 v[118:119], v[118:119], 0, s[98:99]
	v_mfma_f32_32x32x16_bf16 v[50:65], v[206:209], v[218:221], v[50:65]
	s_add_u32 m0, s27, 0x7000
	s_nop 0
	global_load_lds_dwordx4 v[244:245], off
	v_lshl_add_u64 v[244:245], v[244:245], 0, s[98:99]
	v_mfma_f32_32x32x16_bf16 v[2:17], v[210:213], v[214:217], v[2:17]
	v_mfma_f32_32x32x16_bf16 v[18:33], v[210:213], v[218:221], v[18:33]
	s_waitcnt vmcnt(8) lgkmcnt(0)
	s_barrier
	ds_read_b128 v[206:209], v98
	ds_read_b128 v[210:213], v98 offset:4096
	ds_read_b128 v[214:217], v102 offset:49152
	ds_read_b128 v[218:221], v102 offset:57344
	v_mfma_f32_32x32x16_bf16 v[34:49], v[222:225], v[230:233], v[34:49]
	v_mfma_f32_32x32x16_bf16 v[50:65], v[222:225], v[234:237], v[50:65]
	v_mfma_f32_32x32x16_bf16 v[2:17], v[226:229], v[230:233], v[2:17]
	v_mfma_f32_32x32x16_bf16 v[18:33], v[226:229], v[234:237], v[18:33]
	ds_read_b128 v[222:225], v99
	ds_read_b128 v[226:229], v99 offset:4096
	ds_read_b128 v[230:233], v103 offset:49152
	ds_read_b128 v[234:237], v103 offset:57344
	s_waitcnt lgkmcnt(4)
	v_mfma_f32_32x32x16_bf16 v[132:147], v[206:209], v[214:217], v[132:147]
	s_add_u32 m0, s27, 0x8000
	s_nop 0
	global_load_lds_dwordx4 v[120:121], off
	v_lshl_add_u64 v[120:121], v[120:121], 0, s[98:99]
	v_mfma_f32_32x32x16_bf16 v[148:163], v[206:209], v[218:221], v[148:163]
	s_add_u32 m0, s27, 0x9000
	s_nop 0
	global_load_lds_dwordx4 v[122:123], off
	v_lshl_add_u64 v[122:123], v[122:123], 0, s[98:99]
	v_mfma_f32_32x32x16_bf16 v[164:179], v[210:213], v[214:217], v[164:179]
	v_mfma_f32_32x32x16_bf16 v[180:195], v[210:213], v[218:221], v[180:195]
	ds_read_b128 v[206:209], v100
	ds_read_b128 v[210:213], v100 offset:4096
	ds_read_b128 v[214:217], v104 offset:49152
	ds_read_b128 v[218:221], v104 offset:57344
	s_waitcnt lgkmcnt(4)
	v_mfma_f32_32x32x16_bf16 v[132:147], v[222:225], v[230:233], v[132:147]
	s_add_u32 m0, s27, 0xa000
	s_nop 0
	global_load_lds_dwordx4 v[124:125], off
	v_lshl_add_u64 v[124:125], v[124:125], 0, s[98:99]
	v_mfma_f32_32x32x16_bf16 v[148:163], v[222:225], v[234:237], v[148:163]
	v_mfma_f32_32x32x16_bf16 v[164:179], v[226:229], v[230:233], v[164:179]
	v_mfma_f32_32x32x16_bf16 v[180:195], v[226:229], v[234:237], v[180:195]
	ds_read_b128 v[222:225], v101
	ds_read_b128 v[226:229], v101 offset:4096
	ds_read_b128 v[230:233], v105 offset:49152
	ds_read_b128 v[234:237], v105 offset:57344
	s_waitcnt lgkmcnt(4)
	v_mfma_f32_32x32x16_bf16 v[132:147], v[206:209], v[214:217], v[132:147]
	s_add_u32 m0, s27, 0xb000
	s_nop 0
	global_load_lds_dwordx4 v[126:127], off
	v_lshl_add_u64 v[126:127], v[126:127], 0, s[98:99]
	v_mfma_f32_32x32x16_bf16 v[148:163], v[206:209], v[218:221], v[148:163]
	v_mfma_f32_32x32x16_bf16 v[164:179], v[210:213], v[214:217], v[164:179]
	v_mfma_f32_32x32x16_bf16 v[180:195], v[210:213], v[218:221], v[180:195]
	s_waitcnt vmcnt(4) lgkmcnt(0)
	s_barrier
	ds_read_b128 v[206:209], v98 offset:16384
	ds_read_b128 v[210:213], v98 offset:20480
	ds_read_b128 v[214:217], v110
	ds_read_b128 v[218:221], v110 offset:8192
	v_mfma_f32_32x32x16_bf16 v[132:147], v[222:225], v[230:233], v[132:147]
	v_mfma_f32_32x32x16_bf16 v[148:163], v[222:225], v[234:237], v[148:163]
	v_mfma_f32_32x32x16_bf16 v[164:179], v[226:229], v[230:233], v[164:179]
	v_mfma_f32_32x32x16_bf16 v[180:195], v[226:229], v[234:237], v[180:195]
	ds_read_b128 v[222:225], v99 offset:16384
	ds_read_b128 v[226:229], v99 offset:20480
	ds_read_b128 v[230:233], v111
	ds_read_b128 v[234:237], v111 offset:8192
	s_waitcnt lgkmcnt(4)
	v_mfma_f32_32x32x16_bf16 v[34:49], v[206:209], v[214:217], v[34:49]
	s_add_u32 m0, s27, 0xc000
	s_nop 0
	global_load_lds_dwordx4 v[246:247], off
	v_lshl_add_u64 v[246:247], v[246:247], 0, s[98:99]
	v_mfma_f32_32x32x16_bf16 v[50:65], v[206:209], v[218:221], v[50:65]
	s_mov_b32 m0, s27
	s_nop 0
	global_load_lds_dwordx4 v[238:239], off
	v_lshl_add_u64 v[238:239], v[238:239], 0, s[98:99]
	v_mfma_f32_32x32x16_bf16 v[2:17], v[210:213], v[214:217], v[2:17]
	s_add_u32 m0, s27, 0xd000
	s_nop 0
	global_load_lds_dwordx4 v[248:249], off
	v_lshl_add_u64 v[248:249], v[248:249], 0, s[98:99]
	v_mfma_f32_32x32x16_bf16 v[18:33], v[210:213], v[218:221], v[18:33]
	ds_read_b128 v[206:209], v100 offset:16384
	ds_read_b128 v[210:213], v100 offset:20480
	ds_read_b128 v[214:217], v128
	ds_read_b128 v[218:221], v128 offset:8192
	s_waitcnt lgkmcnt(4)
	v_mfma_f32_32x32x16_bf16 v[34:49], v[222:225], v[230:233], v[34:49]
	s_add_u32 m0, s27, 0x1000
	s_nop 0
	global_load_lds_dwordx4 v[240:241], off
	v_lshl_add_u64 v[240:241], v[240:241], 0, s[98:99]
	v_mfma_f32_32x32x16_bf16 v[50:65], v[222:225], v[234:237], v[50:65]
	s_add_u32 m0, s27, 0xe000
	s_nop 0
	global_load_lds_dwordx4 v[250:251], off
	v_lshl_add_u64 v[250:251], v[250:251], 0, s[98:99]
	v_mfma_f32_32x32x16_bf16 v[2:17], v[226:229], v[230:233], v[2:17]
	s_add_u32 m0, s27, 0x2000
	s_nop 0
	global_load_lds_dwordx4 v[242:243], off
	v_lshl_add_u64 v[242:243], v[242:243], 0, s[98:99]
	v_mfma_f32_32x32x16_bf16 v[18:33], v[226:229], v[234:237], v[18:33]
	ds_read_b128 v[222:225], v101 offset:16384
	ds_read_b128 v[226:229], v101 offset:20480
	ds_read_b128 v[230:233], v129
	ds_read_b128 v[234:237], v129 offset:8192
	s_waitcnt lgkmcnt(4)
	v_mfma_f32_32x32x16_bf16 v[34:49], v[206:209], v[214:217], v[34:49]
	s_add_u32 m0, s27, 0xf000
	s_nop 0
	global_load_lds_dwordx4 v[118:119], off
	v_lshl_add_u64 v[118:119], v[118:119], 0, s[98:99]
	v_mfma_f32_32x32x16_bf16 v[50:65], v[206:209], v[218:221], v[50:65]
	s_add_u32 m0, s27, 0x3000
	s_nop 0
	global_load_lds_dwordx4 v[244:245], off
	v_lshl_add_u64 v[244:245], v[244:245], 0, s[98:99]
	v_mfma_f32_32x32x16_bf16 v[2:17], v[210:213], v[214:217], v[2:17]
	v_mfma_f32_32x32x16_bf16 v[18:33], v[210:213], v[218:221], v[18:33]
	s_waitcnt vmcnt(8) lgkmcnt(0)
	s_barrier
	ds_read_b128 v[206:209], v98 offset:16384
	ds_read_b128 v[210:213], v98 offset:20480
	ds_read_b128 v[214:217], v102 offset:32768
	ds_read_b128 v[218:221], v102 offset:40960
	v_mfma_f32_32x32x16_bf16 v[34:49], v[222:225], v[230:233], v[34:49]
	v_mfma_f32_32x32x16_bf16 v[50:65], v[222:225], v[234:237], v[50:65]
	v_mfma_f32_32x32x16_bf16 v[2:17], v[226:229], v[230:233], v[2:17]
	v_mfma_f32_32x32x16_bf16 v[18:33], v[226:229], v[234:237], v[18:33]
	ds_read_b128 v[222:225], v99 offset:16384
	ds_read_b128 v[226:229], v99 offset:20480
	ds_read_b128 v[230:233], v103 offset:32768
	ds_read_b128 v[234:237], v103 offset:40960
	s_waitcnt lgkmcnt(4)
	v_mfma_f32_32x32x16_bf16 v[132:147], v[206:209], v[214:217], v[132:147]
	s_add_u32 m0, s27, 0x10000
	s_nop 0
	global_load_lds_dwordx4 v[120:121], off
	v_lshl_add_u64 v[120:121], v[120:121], 0, s[98:99]
	v_mfma_f32_32x32x16_bf16 v[148:163], v[206:209], v[218:221], v[148:163]
	s_add_u32 m0, s27, 0x11000
	s_nop 0
	global_load_lds_dwordx4 v[122:123], off
	v_lshl_add_u64 v[122:123], v[122:123], 0, s[98:99]
	v_mfma_f32_32x32x16_bf16 v[164:179], v[210:213], v[214:217], v[164:179]
	v_mfma_f32_32x32x16_bf16 v[180:195], v[210:213], v[218:221], v[180:195]
	ds_read_b128 v[206:209], v100 offset:16384
	ds_read_b128 v[210:213], v100 offset:20480
	ds_read_b128 v[214:217], v104 offset:32768
	ds_read_b128 v[218:221], v104 offset:40960
	s_waitcnt lgkmcnt(4)
	v_mfma_f32_32x32x16_bf16 v[132:147], v[222:225], v[230:233], v[132:147]
	s_add_u32 m0, s27, 0x12000
	s_nop 0
	global_load_lds_dwordx4 v[124:125], off
	v_lshl_add_u64 v[124:125], v[124:125], 0, s[98:99]
	v_mfma_f32_32x32x16_bf16 v[148:163], v[222:225], v[234:237], v[148:163]
	v_mfma_f32_32x32x16_bf16 v[164:179], v[226:229], v[230:233], v[164:179]
	v_mfma_f32_32x32x16_bf16 v[180:195], v[226:229], v[234:237], v[180:195]
	ds_read_b128 v[222:225], v101 offset:16384
	ds_read_b128 v[226:229], v101 offset:20480
	ds_read_b128 v[230:233], v105 offset:32768
	ds_read_b128 v[234:237], v105 offset:40960
	s_waitcnt lgkmcnt(4)
	v_mfma_f32_32x32x16_bf16 v[132:147], v[206:209], v[214:217], v[132:147]
	s_add_u32 m0, s27, 0x13000
	s_nop 0
	global_load_lds_dwordx4 v[126:127], off
	v_lshl_add_u64 v[126:127], v[126:127], 0, s[98:99]
	v_mfma_f32_32x32x16_bf16 v[148:163], v[206:209], v[218:221], v[148:163]
	v_mfma_f32_32x32x16_bf16 v[164:179], v[210:213], v[214:217], v[164:179]
	v_mfma_f32_32x32x16_bf16 v[180:195], v[210:213], v[218:221], v[180:195]
	s_waitcnt vmcnt(4) lgkmcnt(0)
	s_barrier
	ds_read_b128 v[206:209], v98
	ds_read_b128 v[210:213], v98 offset:4096
	ds_read_b128 v[214:217], v102 offset:49152
	ds_read_b128 v[218:221], v102 offset:57344
	v_mfma_f32_32x32x16_bf16 v[132:147], v[222:225], v[230:233], v[132:147]
	v_mfma_f32_32x32x16_bf16 v[148:163], v[222:225], v[234:237], v[148:163]
	v_mfma_f32_32x32x16_bf16 v[164:179], v[226:229], v[230:233], v[164:179]
	v_mfma_f32_32x32x16_bf16 v[180:195], v[226:229], v[234:237], v[180:195]
	ds_read_b128 v[222:225], v99
	ds_read_b128 v[226:229], v99 offset:4096
	ds_read_b128 v[230:233], v103 offset:49152
	ds_read_b128 v[234:237], v103 offset:57344
	s_waitcnt lgkmcnt(4)
	v_mfma_f32_32x32x16_bf16 v[34:49], v[206:209], v[214:217], v[34:49]
	s_add_u32 m0, s27, 0x8000
	s_nop 0
	global_load_lds_dwordx4 v[246:247], off
	v_lshl_add_u64 v[246:247], v[246:247], 0, s[98:99]
	v_mfma_f32_32x32x16_bf16 v[50:65], v[206:209], v[218:221], v[50:65]
	s_add_u32 m0, s27, 0x4000
	s_nop 0
	global_load_lds_dwordx4 v[238:239], off
	v_lshl_add_u64 v[238:239], v[238:239], 0, s[98:99]
	v_mfma_f32_32x32x16_bf16 v[2:17], v[210:213], v[214:217], v[2:17]
	s_add_u32 m0, s27, 0x9000
	s_nop 0
	global_load_lds_dwordx4 v[248:249], off
	v_lshl_add_u64 v[248:249], v[248:249], 0, s[98:99]
	v_mfma_f32_32x32x16_bf16 v[18:33], v[210:213], v[218:221], v[18:33]
	ds_read_b128 v[206:209], v100
	ds_read_b128 v[210:213], v100 offset:4096
	ds_read_b128 v[214:217], v104 offset:49152
	ds_read_b128 v[218:221], v104 offset:57344
	s_waitcnt lgkmcnt(4)
	v_mfma_f32_32x32x16_bf16 v[34:49], v[222:225], v[230:233], v[34:49]
	s_add_u32 m0, s27, 0x5000
	s_nop 0
	global_load_lds_dwordx4 v[240:241], off
	v_lshl_add_u64 v[240:241], v[240:241], 0, s[98:99]
	v_mfma_f32_32x32x16_bf16 v[50:65], v[222:225], v[234:237], v[50:65]
	s_add_u32 m0, s27, 0xa000
	s_nop 0
	global_load_lds_dwordx4 v[250:251], off
	v_lshl_add_u64 v[250:251], v[250:251], 0, s[98:99]
	v_mfma_f32_32x32x16_bf16 v[2:17], v[226:229], v[230:233], v[2:17]
	s_add_u32 m0, s27, 0x6000
	s_nop 0
	global_load_lds_dwordx4 v[242:243], off
	v_lshl_add_u64 v[242:243], v[242:243], 0, s[98:99]
	v_mfma_f32_32x32x16_bf16 v[18:33], v[226:229], v[234:237], v[18:33]
	ds_read_b128 v[222:225], v101
	ds_read_b128 v[226:229], v101 offset:4096
	ds_read_b128 v[230:233], v105 offset:49152
	ds_read_b128 v[234:237], v105 offset:57344
	s_waitcnt lgkmcnt(4)
	v_mfma_f32_32x32x16_bf16 v[34:49], v[206:209], v[214:217], v[34:49]
	s_add_u32 m0, s27, 0xb000
	s_nop 0
	global_load_lds_dwordx4 v[118:119], off
	v_lshl_add_u64 v[118:119], v[118:119], 0, s[98:99]
	v_mfma_f32_32x32x16_bf16 v[50:65], v[206:209], v[218:221], v[50:65]
	s_add_u32 m0, s27, 0x7000
	s_nop 0
	global_load_lds_dwordx4 v[244:245], off
	v_lshl_add_u64 v[244:245], v[244:245], 0, s[98:99]
	v_mfma_f32_32x32x16_bf16 v[2:17], v[210:213], v[214:217], v[2:17]
	v_mfma_f32_32x32x16_bf16 v[18:33], v[210:213], v[218:221], v[18:33]
	s_waitcnt vmcnt(8) lgkmcnt(0)
	s_barrier
	ds_read_b128 v[206:209], v98
	ds_read_b128 v[210:213], v98 offset:4096
	ds_read_b128 v[214:217], v110
	ds_read_b128 v[218:221], v110 offset:8192
	v_mfma_f32_32x32x16_bf16 v[34:49], v[222:225], v[230:233], v[34:49]
	v_mfma_f32_32x32x16_bf16 v[50:65], v[222:225], v[234:237], v[50:65]
	v_mfma_f32_32x32x16_bf16 v[2:17], v[226:229], v[230:233], v[2:17]
	v_mfma_f32_32x32x16_bf16 v[18:33], v[226:229], v[234:237], v[18:33]
	ds_read_b128 v[222:225], v99
	ds_read_b128 v[226:229], v99 offset:4096
	ds_read_b128 v[230:233], v111
	ds_read_b128 v[234:237], v111 offset:8192
	s_waitcnt lgkmcnt(4)
	v_mfma_f32_32x32x16_bf16 v[132:147], v[206:209], v[214:217], v[132:147]
	s_add_u32 m0, s27, 0xc000
	s_nop 0
	global_load_lds_dwordx4 v[120:121], off
	v_lshl_add_u64 v[120:121], v[120:121], 0, s[98:99]
	v_mfma_f32_32x32x16_bf16 v[148:163], v[206:209], v[218:221], v[148:163]
	s_add_u32 m0, s27, 0xd000
	s_nop 0
	global_load_lds_dwordx4 v[122:123], off
	v_lshl_add_u64 v[122:123], v[122:123], 0, s[98:99]
	v_mfma_f32_32x32x16_bf16 v[164:179], v[210:213], v[214:217], v[164:179]
	v_mfma_f32_32x32x16_bf16 v[180:195], v[210:213], v[218:221], v[180:195]
	ds_read_b128 v[206:209], v100
	ds_read_b128 v[210:213], v100 offset:4096
	ds_read_b128 v[214:217], v128
	ds_read_b128 v[218:221], v128 offset:8192
	s_waitcnt lgkmcnt(4)
	v_mfma_f32_32x32x16_bf16 v[132:147], v[222:225], v[230:233], v[132:147]
	s_add_u32 m0, s27, 0xe000
	s_nop 0
	global_load_lds_dwordx4 v[124:125], off
	v_lshl_add_u64 v[124:125], v[124:125], 0, s[98:99]
	v_mfma_f32_32x32x16_bf16 v[148:163], v[222:225], v[234:237], v[148:163]
	v_mfma_f32_32x32x16_bf16 v[164:179], v[226:229], v[230:233], v[164:179]
	v_mfma_f32_32x32x16_bf16 v[180:195], v[226:229], v[234:237], v[180:195]
	ds_read_b128 v[222:225], v101
	ds_read_b128 v[226:229], v101 offset:4096
	ds_read_b128 v[230:233], v129
	ds_read_b128 v[234:237], v129 offset:8192
	s_waitcnt lgkmcnt(4)
	v_mfma_f32_32x32x16_bf16 v[132:147], v[206:209], v[214:217], v[132:147]
	s_add_u32 m0, s27, 0xf000
	s_nop 0
	global_load_lds_dwordx4 v[126:127], off
	v_lshl_add_u64 v[126:127], v[126:127], 0, s[98:99]
	v_mfma_f32_32x32x16_bf16 v[148:163], v[206:209], v[218:221], v[148:163]
	v_mfma_f32_32x32x16_bf16 v[164:179], v[210:213], v[214:217], v[164:179]
	v_mfma_f32_32x32x16_bf16 v[180:195], v[210:213], v[218:221], v[180:195]
	s_waitcnt vmcnt(4) lgkmcnt(0)
	s_barrier
	ds_read_b128 v[206:209], v98 offset:16384
	ds_read_b128 v[210:213], v98 offset:20480
	ds_read_b128 v[214:217], v102 offset:32768
	ds_read_b128 v[218:221], v102 offset:40960
	v_mfma_f32_32x32x16_bf16 v[132:147], v[222:225], v[230:233], v[132:147]
	v_mfma_f32_32x32x16_bf16 v[148:163], v[222:225], v[234:237], v[148:163]
	v_mfma_f32_32x32x16_bf16 v[164:179], v[226:229], v[230:233], v[164:179]
	v_mfma_f32_32x32x16_bf16 v[180:195], v[226:229], v[234:237], v[180:195]
	ds_read_b128 v[222:225], v99 offset:16384
	ds_read_b128 v[226:229], v99 offset:20480
	ds_read_b128 v[230:233], v103 offset:32768
	ds_read_b128 v[234:237], v103 offset:40960
	s_waitcnt lgkmcnt(4)
	v_mfma_f32_32x32x16_bf16 v[34:49], v[206:209], v[214:217], v[34:49]
	v_mfma_f32_32x32x16_bf16 v[50:65], v[206:209], v[218:221], v[50:65]
	v_mfma_f32_32x32x16_bf16 v[2:17], v[210:213], v[214:217], v[2:17]
	v_mfma_f32_32x32x16_bf16 v[18:33], v[210:213], v[218:221], v[18:33]
	ds_read_b128 v[206:209], v100 offset:16384
	ds_read_b128 v[210:213], v100 offset:20480
	ds_read_b128 v[214:217], v104 offset:32768
	ds_read_b128 v[218:221], v104 offset:40960
	s_waitcnt lgkmcnt(4)
	v_mfma_f32_32x32x16_bf16 v[34:49], v[222:225], v[230:233], v[34:49]
	v_mfma_f32_32x32x16_bf16 v[50:65], v[222:225], v[234:237], v[50:65]
	v_mfma_f32_32x32x16_bf16 v[2:17], v[226:229], v[230:233], v[2:17]
	v_mfma_f32_32x32x16_bf16 v[18:33], v[226:229], v[234:237], v[18:33]
	ds_read_b128 v[222:225], v101 offset:16384
	ds_read_b128 v[226:229], v101 offset:20480
	ds_read_b128 v[230:233], v105 offset:32768
	ds_read_b128 v[234:237], v105 offset:40960
	s_waitcnt lgkmcnt(4)
	v_mfma_f32_32x32x16_bf16 v[34:49], v[206:209], v[214:217], v[34:49]
	v_mfma_f32_32x32x16_bf16 v[50:65], v[206:209], v[218:221], v[50:65]
	v_mfma_f32_32x32x16_bf16 v[2:17], v[210:213], v[214:217], v[2:17]
	v_mfma_f32_32x32x16_bf16 v[18:33], v[210:213], v[218:221], v[18:33]
	s_waitcnt vmcnt(0) lgkmcnt(0)
	s_barrier
	ds_read_b128 v[206:209], v98 offset:16384
	ds_read_b128 v[210:213], v98 offset:20480
	ds_read_b128 v[214:217], v102 offset:49152
	ds_read_b128 v[218:221], v102 offset:57344
	v_mfma_f32_32x32x16_bf16 v[34:49], v[222:225], v[230:233], v[34:49]
	v_mfma_f32_32x32x16_bf16 v[50:65], v[222:225], v[234:237], v[50:65]
	v_mfma_f32_32x32x16_bf16 v[2:17], v[226:229], v[230:233], v[2:17]
	v_mfma_f32_32x32x16_bf16 v[18:33], v[226:229], v[234:237], v[18:33]
	ds_read_b128 v[222:225], v99 offset:16384
	ds_read_b128 v[226:229], v99 offset:20480
	ds_read_b128 v[230:233], v103 offset:49152
	ds_read_b128 v[234:237], v103 offset:57344
	s_waitcnt lgkmcnt(4)
	v_mfma_f32_32x32x16_bf16 v[132:147], v[206:209], v[214:217], v[132:147]
	v_mfma_f32_32x32x16_bf16 v[148:163], v[206:209], v[218:221], v[148:163]
	v_mfma_f32_32x32x16_bf16 v[164:179], v[210:213], v[214:217], v[164:179]
	v_mfma_f32_32x32x16_bf16 v[180:195], v[210:213], v[218:221], v[180:195]
	ds_read_b128 v[206:209], v100 offset:16384
	ds_read_b128 v[210:213], v100 offset:20480
	ds_read_b128 v[214:217], v104 offset:49152
	ds_read_b128 v[218:221], v104 offset:57344
	s_waitcnt lgkmcnt(4)
	v_mfma_f32_32x32x16_bf16 v[132:147], v[222:225], v[230:233], v[132:147]
	v_mfma_f32_32x32x16_bf16 v[148:163], v[222:225], v[234:237], v[148:163]
	v_mfma_f32_32x32x16_bf16 v[164:179], v[226:229], v[230:233], v[164:179]
	v_mfma_f32_32x32x16_bf16 v[180:195], v[226:229], v[234:237], v[180:195]
	ds_read_b128 v[222:225], v101 offset:16384
	ds_read_b128 v[226:229], v101 offset:20480
	ds_read_b128 v[230:233], v105 offset:49152
	ds_read_b128 v[234:237], v105 offset:57344
	s_waitcnt lgkmcnt(4)
	v_mfma_f32_32x32x16_bf16 v[132:147], v[206:209], v[214:217], v[132:147]
	v_mfma_f32_32x32x16_bf16 v[148:163], v[206:209], v[218:221], v[148:163]
	v_mfma_f32_32x32x16_bf16 v[164:179], v[210:213], v[214:217], v[164:179]
	v_mfma_f32_32x32x16_bf16 v[180:195], v[210:213], v[218:221], v[180:195]
	s_waitcnt lgkmcnt(0)
	s_barrier
	v_mfma_f32_32x32x16_bf16 v[132:147], v[222:225], v[230:233], v[132:147]
	v_mfma_f32_32x32x16_bf16 v[148:163], v[222:225], v[234:237], v[148:163]
	v_mfma_f32_32x32x16_bf16 v[164:179], v[226:229], v[230:233], v[164:179]
	v_mfma_f32_32x32x16_bf16 v[180:195], v[226:229], v[234:237], v[180:195]
	s_nop 15
.Lg1_epi:
	v_mul_f32_e32 v79, 0xbfb8aa3b, v34
	v_exp_f32_e32 v79, v79
	v_or_b32_e32 v76, s4, v88
	v_ashrrev_i32_e32 v77, 31, v76
	v_lshl_add_u64 v[76:77], v[76:77], 1, s[8:9]
	v_add_f32_e32 v79, 1.0, v79
	v_add_u32_e32 v78, s1, v97
	v_div_scale_f32 v80, s[4:5], v79, v79, v34
	v_rcp_f32_e32 v81, v80
	s_nop 0
	v_fma_f32 v82, -v80, v81, 1.0
	v_fmac_f32_e32 v81, v82, v81
	v_div_scale_f32 v82, vcc, v34, v79, v34
	v_mul_f32_e32 v83, v82, v81
	v_fma_f32 v84, -v80, v83, v82
	v_fmac_f32_e32 v83, v84, v81
	v_fma_f32 v80, -v80, v83, v82
	v_div_fmas_f32 v80, v80, v81, v83
	v_div_fixup_f32 v34, v80, v79, v34
	v_mul_f32_e32 v34, v50, v34
	v_bfe_u32 v50, v34, 16, 1
	v_add3_u32 v34, v34, v50, s26
	v_mul_f32_e32 v50, 0xbfb8aa3b, v35
	v_exp_f32_e32 v50, v50
	v_mad_i64_i32 v[80:81], s[4:5], v78, s50, v[76:77]
	global_store_short_d16_hi v[80:81], v34, off
	v_add_f32_e32 v50, 1.0, v50
	v_div_scale_f32 v79, s[4:5], v50, v50, v35
	v_rcp_f32_e32 v80, v79
	v_or_b32_e32 v34, 1, v78
	v_fma_f32 v81, -v79, v80, 1.0
	v_fmac_f32_e32 v80, v81, v80
	v_div_scale_f32 v81, vcc, v35, v50, v35
	v_mul_f32_e32 v82, v81, v80
	v_fma_f32 v83, -v79, v82, v81
	v_fmac_f32_e32 v82, v83, v80
	v_fma_f32 v79, -v79, v82, v81
	v_div_fmas_f32 v79, v79, v80, v82
	v_div_fixup_f32 v35, v79, v50, v35
	v_mul_f32_e32 v35, v51, v35
	v_bfe_u32 v50, v35, 16, 1
	v_add3_u32 v50, v35, v50, s26
	v_mad_i64_i32 v[34:35], s[4:5], v34, s50, v[76:77]
	global_store_short_d16_hi v[34:35], v50, off
	v_mul_f32_e32 v35, 0xbfb8aa3b, v36
	v_exp_f32_e32 v35, v35
	v_or_b32_e32 v34, 2, v78
	v_add_f32_e32 v35, 1.0, v35
	v_div_scale_f32 v50, s[4:5], v35, v35, v36
	v_rcp_f32_e32 v51, v50
	s_nop 0
	v_fma_f32 v79, -v50, v51, 1.0
	v_fmac_f32_e32 v51, v79, v51
	v_div_scale_f32 v79, vcc, v36, v35, v36
	v_mul_f32_e32 v80, v79, v51
	v_fma_f32 v81, -v50, v80, v79
	v_fmac_f32_e32 v80, v81, v51
	v_fma_f32 v50, -v50, v80, v79
	v_div_fmas_f32 v50, v50, v51, v80
	v_div_fixup_f32 v35, v50, v35, v36
	v_mul_f32_e32 v35, v52, v35
	v_bfe_u32 v36, v35, 16, 1
	v_add3_u32 v36, v35, v36, s26
	v_mad_i64_i32 v[34:35], s[4:5], v34, s50, v[76:77]
	global_store_short_d16_hi v[34:35], v36, off
	v_mul_f32_e32 v35, 0xbfb8aa3b, v37
	v_exp_f32_e32 v35, v35
	v_or_b32_e32 v34, 3, v78
	v_add_f32_e32 v35, 1.0, v35
	v_div_scale_f32 v36, s[4:5], v35, v35, v37
	v_rcp_f32_e32 v50, v36
	s_nop 0
	v_fma_f32 v51, -v36, v50, 1.0
	v_fmac_f32_e32 v50, v51, v50
	v_div_scale_f32 v51, vcc, v37, v35, v37
	v_mul_f32_e32 v52, v51, v50
	v_fma_f32 v79, -v36, v52, v51
	v_fmac_f32_e32 v52, v79, v50
	v_fma_f32 v36, -v36, v52, v51
	v_div_fmas_f32 v36, v36, v50, v52
	v_div_fixup_f32 v35, v36, v35, v37
	v_mul_f32_e32 v35, v53, v35
	v_bfe_u32 v36, v35, 16, 1
	v_add3_u32 v36, v35, v36, s26
	v_mad_i64_i32 v[34:35], s[4:5], v34, s50, v[76:77]
	global_store_short_d16_hi v[34:35], v36, off
	v_mul_f32_e32 v35, 0xbfb8aa3b, v38
	v_exp_f32_e32 v35, v35
	v_or_b32_e32 v34, 8, v78
	v_add_f32_e32 v35, 1.0, v35
	v_div_scale_f32 v36, s[4:5], v35, v35, v38
	v_rcp_f32_e32 v37, v36
	s_nop 0
	v_fma_f32 v50, -v36, v37, 1.0
	v_fmac_f32_e32 v37, v50, v37
	v_div_scale_f32 v50, vcc, v38, v35, v38
	v_mul_f32_e32 v51, v50, v37
	v_fma_f32 v52, -v36, v51, v50
	v_fmac_f32_e32 v51, v52, v37
	v_fma_f32 v36, -v36, v51, v50
	v_div_fmas_f32 v36, v36, v37, v51
	v_div_fixup_f32 v35, v36, v35, v38
	v_mul_f32_e32 v35, v54, v35
	v_bfe_u32 v36, v35, 16, 1
	v_add3_u32 v36, v35, v36, s26
	v_mad_i64_i32 v[34:35], s[4:5], v34, s50, v[76:77]
	global_store_short_d16_hi v[34:35], v36, off
	v_mul_f32_e32 v35, 0xbfb8aa3b, v39
	v_exp_f32_e32 v35, v35
	v_or_b32_e32 v34, 9, v78
	v_add_f32_e32 v35, 1.0, v35
	v_div_scale_f32 v36, s[4:5], v35, v35, v39
	v_rcp_f32_e32 v37, v36
	s_nop 0
	v_fma_f32 v38, -v36, v37, 1.0
	v_fmac_f32_e32 v37, v38, v37
	v_div_scale_f32 v38, vcc, v39, v35, v39
	v_mul_f32_e32 v50, v38, v37
	v_fma_f32 v51, -v36, v50, v38
	v_fmac_f32_e32 v50, v51, v37
	v_fma_f32 v36, -v36, v50, v38
	v_div_fmas_f32 v36, v36, v37, v50
	v_div_fixup_f32 v35, v36, v35, v39
	v_mul_f32_e32 v35, v55, v35
	v_bfe_u32 v36, v35, 16, 1
	v_add3_u32 v36, v35, v36, s26
	v_mad_i64_i32 v[34:35], s[4:5], v34, s50, v[76:77]
	global_store_short_d16_hi v[34:35], v36, off
	v_mul_f32_e32 v35, 0xbfb8aa3b, v40
	v_exp_f32_e32 v35, v35
	v_or_b32_e32 v34, 10, v78
	v_add_f32_e32 v35, 1.0, v35
	v_div_scale_f32 v36, s[4:5], v35, v35, v40
	v_rcp_f32_e32 v37, v36
	s_nop 0
	v_fma_f32 v38, -v36, v37, 1.0
	v_fmac_f32_e32 v37, v38, v37
	v_div_scale_f32 v38, vcc, v40, v35, v40
	v_mul_f32_e32 v39, v38, v37
	v_fma_f32 v50, -v36, v39, v38
	v_fmac_f32_e32 v39, v50, v37
	v_fma_f32 v36, -v36, v39, v38
	v_div_fmas_f32 v36, v36, v37, v39
	v_div_fixup_f32 v35, v36, v35, v40
	v_mul_f32_e32 v35, v56, v35
	v_bfe_u32 v36, v35, 16, 1
	v_add3_u32 v36, v35, v36, s26
	v_mad_i64_i32 v[34:35], s[4:5], v34, s50, v[76:77]
	global_store_short_d16_hi v[34:35], v36, off
	v_mul_f32_e32 v35, 0xbfb8aa3b, v41
	v_exp_f32_e32 v35, v35
	v_or_b32_e32 v34, 11, v78
	v_add_f32_e32 v35, 1.0, v35
	v_div_scale_f32 v36, s[4:5], v35, v35, v41
	v_rcp_f32_e32 v37, v36
	s_nop 0
	v_fma_f32 v38, -v36, v37, 1.0
	v_fmac_f32_e32 v37, v38, v37
	v_div_scale_f32 v38, vcc, v41, v35, v41
	v_mul_f32_e32 v39, v38, v37
	v_fma_f32 v40, -v36, v39, v38
	v_fmac_f32_e32 v39, v40, v37
	v_fma_f32 v36, -v36, v39, v38
	v_div_fmas_f32 v36, v36, v37, v39
	v_div_fixup_f32 v35, v36, v35, v41
	v_mul_f32_e32 v35, v57, v35
	v_bfe_u32 v36, v35, 16, 1
	v_add3_u32 v36, v35, v36, s26
	v_mad_i64_i32 v[34:35], s[4:5], v34, s50, v[76:77]
	global_store_short_d16_hi v[34:35], v36, off
	v_mul_f32_e32 v35, 0xbfb8aa3b, v42
	v_exp_f32_e32 v35, v35
	v_or_b32_e32 v34, 16, v78
	v_add_f32_e32 v35, 1.0, v35
	v_div_scale_f32 v36, s[4:5], v35, v35, v42
	v_rcp_f32_e32 v37, v36
	s_nop 0
	v_fma_f32 v38, -v36, v37, 1.0
	v_fmac_f32_e32 v37, v38, v37
	v_div_scale_f32 v38, vcc, v42, v35, v42
	v_mul_f32_e32 v39, v38, v37
	v_fma_f32 v40, -v36, v39, v38
	v_fmac_f32_e32 v39, v40, v37
	v_fma_f32 v36, -v36, v39, v38
	v_div_fmas_f32 v36, v36, v37, v39
	v_div_fixup_f32 v35, v36, v35, v42
	v_mul_f32_e32 v35, v58, v35
	v_bfe_u32 v36, v35, 16, 1
	v_add3_u32 v36, v35, v36, s26
	v_mad_i64_i32 v[34:35], s[4:5], v34, s50, v[76:77]
	global_store_short_d16_hi v[34:35], v36, off
	v_mul_f32_e32 v35, 0xbfb8aa3b, v43
	v_exp_f32_e32 v35, v35
	v_or_b32_e32 v34, 17, v78
	v_add_f32_e32 v35, 1.0, v35
	v_div_scale_f32 v36, s[4:5], v35, v35, v43
	v_rcp_f32_e32 v37, v36
	s_nop 0
	v_fma_f32 v38, -v36, v37, 1.0
	v_fmac_f32_e32 v37, v38, v37
	v_div_scale_f32 v38, vcc, v43, v35, v43
	v_mul_f32_e32 v39, v38, v37
	v_fma_f32 v40, -v36, v39, v38
	v_fmac_f32_e32 v39, v40, v37
	v_fma_f32 v36, -v36, v39, v38
	v_div_fmas_f32 v36, v36, v37, v39
	v_div_fixup_f32 v35, v36, v35, v43
	v_mul_f32_e32 v35, v59, v35
	v_bfe_u32 v36, v35, 16, 1
	v_add3_u32 v36, v35, v36, s26
	v_mad_i64_i32 v[34:35], s[4:5], v34, s50, v[76:77]
	global_store_short_d16_hi v[34:35], v36, off
	v_mul_f32_e32 v35, 0xbfb8aa3b, v44
	v_exp_f32_e32 v35, v35
	v_or_b32_e32 v34, 18, v78
	v_add_f32_e32 v35, 1.0, v35
	v_div_scale_f32 v36, s[4:5], v35, v35, v44
	v_rcp_f32_e32 v37, v36
	s_nop 0
	v_fma_f32 v38, -v36, v37, 1.0
	v_fmac_f32_e32 v37, v38, v37
	v_div_scale_f32 v38, vcc, v44, v35, v44
	v_mul_f32_e32 v39, v38, v37
	v_fma_f32 v40, -v36, v39, v38
	v_fmac_f32_e32 v39, v40, v37
	v_fma_f32 v36, -v36, v39, v38
	v_div_fmas_f32 v36, v36, v37, v39
	v_div_fixup_f32 v35, v36, v35, v44
	v_mul_f32_e32 v35, v60, v35
	v_bfe_u32 v36, v35, 16, 1
	v_add3_u32 v36, v35, v36, s26
	v_mad_i64_i32 v[34:35], s[4:5], v34, s50, v[76:77]
	global_store_short_d16_hi v[34:35], v36, off
	v_mul_f32_e32 v35, 0xbfb8aa3b, v45
	v_exp_f32_e32 v35, v35
	v_or_b32_e32 v34, 19, v78
	v_add_f32_e32 v35, 1.0, v35
	v_div_scale_f32 v36, s[4:5], v35, v35, v45
	v_rcp_f32_e32 v37, v36
	s_nop 0
	v_fma_f32 v38, -v36, v37, 1.0
	v_fmac_f32_e32 v37, v38, v37
	v_div_scale_f32 v38, vcc, v45, v35, v45
	v_mul_f32_e32 v39, v38, v37
	v_fma_f32 v40, -v36, v39, v38
	v_fmac_f32_e32 v39, v40, v37
	v_fma_f32 v36, -v36, v39, v38
	v_div_fmas_f32 v36, v36, v37, v39
	v_div_fixup_f32 v35, v36, v35, v45
	v_mul_f32_e32 v35, v61, v35
	v_bfe_u32 v36, v35, 16, 1
	v_add3_u32 v36, v35, v36, s26
	v_mad_i64_i32 v[34:35], s[4:5], v34, s50, v[76:77]
	global_store_short_d16_hi v[34:35], v36, off
	v_mul_f32_e32 v35, 0xbfb8aa3b, v46
	v_exp_f32_e32 v35, v35
	v_or_b32_e32 v34, 24, v78
	v_add_f32_e32 v35, 1.0, v35
	v_div_scale_f32 v36, s[4:5], v35, v35, v46
	v_rcp_f32_e32 v37, v36
	s_nop 0
	v_fma_f32 v38, -v36, v37, 1.0
	v_fmac_f32_e32 v37, v38, v37
	v_div_scale_f32 v38, vcc, v46, v35, v46
	v_mul_f32_e32 v39, v38, v37
	v_fma_f32 v40, -v36, v39, v38
	v_fmac_f32_e32 v39, v40, v37
	v_fma_f32 v36, -v36, v39, v38
	v_div_fmas_f32 v36, v36, v37, v39
	v_div_fixup_f32 v35, v36, v35, v46
	v_mul_f32_e32 v35, v62, v35
	v_bfe_u32 v36, v35, 16, 1
	v_add3_u32 v36, v35, v36, s26
	v_mad_i64_i32 v[34:35], s[4:5], v34, s50, v[76:77]
	global_store_short_d16_hi v[34:35], v36, off
	v_mul_f32_e32 v35, 0xbfb8aa3b, v47
	v_exp_f32_e32 v35, v35
	v_or_b32_e32 v34, 25, v78
	v_add_f32_e32 v35, 1.0, v35
	v_div_scale_f32 v36, s[4:5], v35, v35, v47
	v_rcp_f32_e32 v37, v36
	s_nop 0
	v_fma_f32 v38, -v36, v37, 1.0
	v_fmac_f32_e32 v37, v38, v37
	v_div_scale_f32 v38, vcc, v47, v35, v47
	v_mul_f32_e32 v39, v38, v37
	v_fma_f32 v40, -v36, v39, v38
	v_fmac_f32_e32 v39, v40, v37
	v_fma_f32 v36, -v36, v39, v38
	v_div_fmas_f32 v36, v36, v37, v39
	v_div_fixup_f32 v35, v36, v35, v47
	v_mul_f32_e32 v35, v63, v35
	v_bfe_u32 v36, v35, 16, 1
	v_add3_u32 v36, v35, v36, s26
	v_mad_i64_i32 v[34:35], s[4:5], v34, s50, v[76:77]
	global_store_short_d16_hi v[34:35], v36, off
	v_mul_f32_e32 v35, 0xbfb8aa3b, v48
	v_exp_f32_e32 v35, v35
	v_or_b32_e32 v34, 26, v78
	v_add_f32_e32 v35, 1.0, v35
	v_div_scale_f32 v36, s[4:5], v35, v35, v48
	v_rcp_f32_e32 v37, v36
	s_nop 0
	v_fma_f32 v38, -v36, v37, 1.0
	v_fmac_f32_e32 v37, v38, v37
	v_div_scale_f32 v38, vcc, v48, v35, v48
	v_mul_f32_e32 v39, v38, v37
	v_fma_f32 v40, -v36, v39, v38
	v_fmac_f32_e32 v39, v40, v37
	v_fma_f32 v36, -v36, v39, v38
	v_div_fmas_f32 v36, v36, v37, v39
	v_div_fixup_f32 v35, v36, v35, v48
	v_mul_f32_e32 v35, v64, v35
	v_bfe_u32 v36, v35, 16, 1
	v_add3_u32 v36, v35, v36, s26
	v_mad_i64_i32 v[34:35], s[4:5], v34, s50, v[76:77]
	global_store_short_d16_hi v[34:35], v36, off
	v_mul_f32_e32 v35, 0xbfb8aa3b, v49
	v_exp_f32_e32 v35, v35
	v_or_b32_e32 v34, 27, v78
	v_add_f32_e32 v35, 1.0, v35
	v_div_scale_f32 v36, s[4:5], v35, v35, v49
	v_rcp_f32_e32 v37, v36
	s_nop 0
	v_fma_f32 v38, -v36, v37, 1.0
	v_fmac_f32_e32 v37, v38, v37
	v_div_scale_f32 v38, vcc, v49, v35, v49
	v_mul_f32_e32 v39, v38, v37
	v_fma_f32 v40, -v36, v39, v38
	v_fmac_f32_e32 v39, v40, v37
	v_fma_f32 v36, -v36, v39, v38
	v_div_fmas_f32 v36, v36, v37, v39
	v_div_fixup_f32 v35, v36, v35, v49
	v_mul_f32_e32 v35, v65, v35
	v_bfe_u32 v36, v35, 16, 1
	v_add3_u32 v36, v35, v36, s26
	v_mad_i64_i32 v[34:35], s[4:5], v34, s50, v[76:77]
	global_store_short_d16_hi v[34:35], v36, off
	v_mul_f32_e32 v35, 0xbfb8aa3b, v2
	v_exp_f32_e32 v35, v35
	v_or_b32_e32 v34, 32, v78
	v_add_f32_e32 v35, 1.0, v35
	v_div_scale_f32 v36, s[4:5], v35, v35, v2
	v_rcp_f32_e32 v37, v36
	s_nop 0
	v_fma_f32 v38, -v36, v37, 1.0
	v_fmac_f32_e32 v37, v38, v37
	v_div_scale_f32 v38, vcc, v2, v35, v2
	v_mul_f32_e32 v39, v38, v37
	v_fma_f32 v40, -v36, v39, v38
	v_fmac_f32_e32 v39, v40, v37
	v_fma_f32 v36, -v36, v39, v38
	v_div_fmas_f32 v36, v36, v37, v39
	v_div_fixup_f32 v2, v36, v35, v2
	v_mul_f32_e32 v2, v18, v2
	v_bfe_u32 v18, v2, 16, 1
	v_add3_u32 v2, v2, v18, s26
	v_mul_f32_e32 v18, 0xbfb8aa3b, v3
	v_exp_f32_e32 v18, v18
	v_mad_i64_i32 v[34:35], s[4:5], v34, s50, v[76:77]
	global_store_short_d16_hi v[34:35], v2, off
	v_add_f32_e32 v18, 1.0, v18
	v_div_scale_f32 v34, s[4:5], v18, v18, v3
	v_rcp_f32_e32 v35, v34
	v_or_b32_e32 v2, 33, v78
	v_fma_f32 v36, -v34, v35, 1.0
	v_fmac_f32_e32 v35, v36, v35
	v_div_scale_f32 v36, vcc, v3, v18, v3
	v_mul_f32_e32 v37, v36, v35
	v_fma_f32 v38, -v34, v37, v36
	v_fmac_f32_e32 v37, v38, v35
	v_fma_f32 v34, -v34, v37, v36
	v_div_fmas_f32 v34, v34, v35, v37
	v_div_fixup_f32 v3, v34, v18, v3
	v_mul_f32_e32 v3, v19, v3
	v_bfe_u32 v18, v3, 16, 1
	v_add3_u32 v18, v3, v18, s26
	v_mad_i64_i32 v[2:3], s[4:5], v2, s50, v[76:77]
	global_store_short_d16_hi v[2:3], v18, off
	v_mul_f32_e32 v3, 0xbfb8aa3b, v4
	v_exp_f32_e32 v3, v3
	v_or_b32_e32 v2, 34, v78
	v_add_f32_e32 v3, 1.0, v3
	v_div_scale_f32 v18, s[4:5], v3, v3, v4
	v_rcp_f32_e32 v19, v18
	s_nop 0
	v_fma_f32 v34, -v18, v19, 1.0
	v_fmac_f32_e32 v19, v34, v19
	v_div_scale_f32 v34, vcc, v4, v3, v4
	v_mul_f32_e32 v35, v34, v19
	v_fma_f32 v36, -v18, v35, v34
	v_fmac_f32_e32 v35, v36, v19
	v_fma_f32 v18, -v18, v35, v34
	v_div_fmas_f32 v18, v18, v19, v35
	v_div_fixup_f32 v3, v18, v3, v4
	v_mul_f32_e32 v3, v20, v3
	v_bfe_u32 v4, v3, 16, 1
	v_add3_u32 v4, v3, v4, s26
	v_mad_i64_i32 v[2:3], s[4:5], v2, s50, v[76:77]
	global_store_short_d16_hi v[2:3], v4, off
	v_mul_f32_e32 v3, 0xbfb8aa3b, v5
	v_exp_f32_e32 v3, v3
	v_or_b32_e32 v2, 35, v78
	v_add_f32_e32 v3, 1.0, v3
	v_div_scale_f32 v4, s[4:5], v3, v3, v5
	v_rcp_f32_e32 v18, v4
	s_nop 0
	v_fma_f32 v19, -v4, v18, 1.0
	v_fmac_f32_e32 v18, v19, v18
	v_div_scale_f32 v19, vcc, v5, v3, v5
	v_mul_f32_e32 v20, v19, v18
	v_fma_f32 v34, -v4, v20, v19
	v_fmac_f32_e32 v20, v34, v18
	v_fma_f32 v4, -v4, v20, v19
	v_div_fmas_f32 v4, v4, v18, v20
	v_div_fixup_f32 v3, v4, v3, v5
	v_mul_f32_e32 v3, v21, v3
	v_bfe_u32 v4, v3, 16, 1
	v_add3_u32 v4, v3, v4, s26
	v_mad_i64_i32 v[2:3], s[4:5], v2, s50, v[76:77]
	global_store_short_d16_hi v[2:3], v4, off
	v_mul_f32_e32 v3, 0xbfb8aa3b, v6
	v_exp_f32_e32 v3, v3
	v_or_b32_e32 v2, 40, v78
	v_add_f32_e32 v3, 1.0, v3
	v_div_scale_f32 v4, s[4:5], v3, v3, v6
	v_rcp_f32_e32 v5, v4
	s_nop 0
	v_fma_f32 v18, -v4, v5, 1.0
	v_fmac_f32_e32 v5, v18, v5
	v_div_scale_f32 v18, vcc, v6, v3, v6
	v_mul_f32_e32 v19, v18, v5
	v_fma_f32 v20, -v4, v19, v18
	v_fmac_f32_e32 v19, v20, v5
	v_fma_f32 v4, -v4, v19, v18
	v_div_fmas_f32 v4, v4, v5, v19
	v_div_fixup_f32 v3, v4, v3, v6
	v_mul_f32_e32 v3, v22, v3
	v_bfe_u32 v4, v3, 16, 1
	v_add3_u32 v4, v3, v4, s26
	v_mad_i64_i32 v[2:3], s[4:5], v2, s50, v[76:77]
	global_store_short_d16_hi v[2:3], v4, off
	v_mul_f32_e32 v3, 0xbfb8aa3b, v7
	v_exp_f32_e32 v3, v3
	v_or_b32_e32 v2, 41, v78
	v_add_f32_e32 v3, 1.0, v3
	v_div_scale_f32 v4, s[4:5], v3, v3, v7
	v_rcp_f32_e32 v5, v4
	s_nop 0
	v_fma_f32 v6, -v4, v5, 1.0
	v_fmac_f32_e32 v5, v6, v5
	v_div_scale_f32 v6, vcc, v7, v3, v7
	v_mul_f32_e32 v18, v6, v5
	v_fma_f32 v19, -v4, v18, v6
	v_fmac_f32_e32 v18, v19, v5
	v_fma_f32 v4, -v4, v18, v6
	v_div_fmas_f32 v4, v4, v5, v18
	v_div_fixup_f32 v3, v4, v3, v7
	v_mul_f32_e32 v3, v23, v3
	v_bfe_u32 v4, v3, 16, 1
	v_add3_u32 v4, v3, v4, s26
	v_mad_i64_i32 v[2:3], s[4:5], v2, s50, v[76:77]
	global_store_short_d16_hi v[2:3], v4, off
	v_mul_f32_e32 v3, 0xbfb8aa3b, v8
	v_exp_f32_e32 v3, v3
	v_or_b32_e32 v2, 42, v78
	v_add_f32_e32 v3, 1.0, v3
	v_div_scale_f32 v4, s[4:5], v3, v3, v8
	v_rcp_f32_e32 v5, v4
	s_nop 0
	v_fma_f32 v6, -v4, v5, 1.0
	v_fmac_f32_e32 v5, v6, v5
	v_div_scale_f32 v6, vcc, v8, v3, v8
	v_mul_f32_e32 v7, v6, v5
	v_fma_f32 v18, -v4, v7, v6
	v_fmac_f32_e32 v7, v18, v5
	v_fma_f32 v4, -v4, v7, v6
	v_div_fmas_f32 v4, v4, v5, v7
	v_div_fixup_f32 v3, v4, v3, v8
	v_mul_f32_e32 v3, v24, v3
	v_bfe_u32 v4, v3, 16, 1
	v_add3_u32 v4, v3, v4, s26
	v_mad_i64_i32 v[2:3], s[4:5], v2, s50, v[76:77]
	global_store_short_d16_hi v[2:3], v4, off
	v_mul_f32_e32 v3, 0xbfb8aa3b, v9
	v_exp_f32_e32 v3, v3
	v_or_b32_e32 v2, 43, v78
	v_add_f32_e32 v3, 1.0, v3
	v_div_scale_f32 v4, s[4:5], v3, v3, v9
	v_rcp_f32_e32 v5, v4
	s_nop 0
	v_fma_f32 v6, -v4, v5, 1.0
	v_fmac_f32_e32 v5, v6, v5
	v_div_scale_f32 v6, vcc, v9, v3, v9
	v_mul_f32_e32 v7, v6, v5
	v_fma_f32 v8, -v4, v7, v6
	v_fmac_f32_e32 v7, v8, v5
	v_fma_f32 v4, -v4, v7, v6
	v_div_fmas_f32 v4, v4, v5, v7
	v_div_fixup_f32 v3, v4, v3, v9
	v_mul_f32_e32 v3, v25, v3
	v_bfe_u32 v4, v3, 16, 1
	v_add3_u32 v4, v3, v4, s26
	v_mad_i64_i32 v[2:3], s[4:5], v2, s50, v[76:77]
	global_store_short_d16_hi v[2:3], v4, off
	v_mul_f32_e32 v3, 0xbfb8aa3b, v10
	v_exp_f32_e32 v3, v3
	v_or_b32_e32 v2, 48, v78
	v_add_f32_e32 v3, 1.0, v3
	v_div_scale_f32 v4, s[4:5], v3, v3, v10
	v_rcp_f32_e32 v5, v4
	s_nop 0
	v_fma_f32 v6, -v4, v5, 1.0
	v_fmac_f32_e32 v5, v6, v5
	v_div_scale_f32 v6, vcc, v10, v3, v10
	v_mul_f32_e32 v7, v6, v5
	v_fma_f32 v8, -v4, v7, v6
	v_fmac_f32_e32 v7, v8, v5
	v_fma_f32 v4, -v4, v7, v6
	v_div_fmas_f32 v4, v4, v5, v7
	v_div_fixup_f32 v3, v4, v3, v10
	v_mul_f32_e32 v3, v26, v3
	v_bfe_u32 v4, v3, 16, 1
	v_add3_u32 v4, v3, v4, s26
	v_mad_i64_i32 v[2:3], s[4:5], v2, s50, v[76:77]
	global_store_short_d16_hi v[2:3], v4, off
	v_mul_f32_e32 v3, 0xbfb8aa3b, v11
	v_exp_f32_e32 v3, v3
	v_or_b32_e32 v2, 49, v78
	v_add_f32_e32 v3, 1.0, v3
	v_div_scale_f32 v4, s[4:5], v3, v3, v11
	v_rcp_f32_e32 v5, v4
	s_nop 0
	v_fma_f32 v6, -v4, v5, 1.0
	v_fmac_f32_e32 v5, v6, v5
	v_div_scale_f32 v6, vcc, v11, v3, v11
	v_mul_f32_e32 v7, v6, v5
	v_fma_f32 v8, -v4, v7, v6
	v_fmac_f32_e32 v7, v8, v5
	v_fma_f32 v4, -v4, v7, v6
	v_div_fmas_f32 v4, v4, v5, v7
	v_div_fixup_f32 v3, v4, v3, v11
	v_mul_f32_e32 v3, v27, v3
	v_bfe_u32 v4, v3, 16, 1
	v_add3_u32 v4, v3, v4, s26
	v_mad_i64_i32 v[2:3], s[4:5], v2, s50, v[76:77]
	global_store_short_d16_hi v[2:3], v4, off
	v_mul_f32_e32 v3, 0xbfb8aa3b, v12
	v_exp_f32_e32 v3, v3
	v_or_b32_e32 v2, 50, v78
	v_add_f32_e32 v3, 1.0, v3
	v_div_scale_f32 v4, s[4:5], v3, v3, v12
	v_rcp_f32_e32 v5, v4
	s_nop 0
	v_fma_f32 v6, -v4, v5, 1.0
	v_fmac_f32_e32 v5, v6, v5
	v_div_scale_f32 v6, vcc, v12, v3, v12
	v_mul_f32_e32 v7, v6, v5
	v_fma_f32 v8, -v4, v7, v6
	v_fmac_f32_e32 v7, v8, v5
	v_fma_f32 v4, -v4, v7, v6
	v_div_fmas_f32 v4, v4, v5, v7
	v_div_fixup_f32 v3, v4, v3, v12
	v_mul_f32_e32 v3, v28, v3
	v_bfe_u32 v4, v3, 16, 1
	v_add3_u32 v4, v3, v4, s26
	v_mad_i64_i32 v[2:3], s[4:5], v2, s50, v[76:77]
	global_store_short_d16_hi v[2:3], v4, off
	v_mul_f32_e32 v3, 0xbfb8aa3b, v13
	v_exp_f32_e32 v3, v3
	v_or_b32_e32 v2, 51, v78
	v_add_f32_e32 v3, 1.0, v3
	v_div_scale_f32 v4, s[4:5], v3, v3, v13
	v_rcp_f32_e32 v5, v4
	s_nop 0
	v_fma_f32 v6, -v4, v5, 1.0
	v_fmac_f32_e32 v5, v6, v5
	v_div_scale_f32 v6, vcc, v13, v3, v13
	v_mul_f32_e32 v7, v6, v5
	v_fma_f32 v8, -v4, v7, v6
	v_fmac_f32_e32 v7, v8, v5
	v_fma_f32 v4, -v4, v7, v6
	v_div_fmas_f32 v4, v4, v5, v7
	v_div_fixup_f32 v3, v4, v3, v13
	v_mul_f32_e32 v3, v29, v3
	v_bfe_u32 v4, v3, 16, 1
	v_add3_u32 v4, v3, v4, s26
	v_mad_i64_i32 v[2:3], s[4:5], v2, s50, v[76:77]
	global_store_short_d16_hi v[2:3], v4, off
	v_mul_f32_e32 v3, 0xbfb8aa3b, v14
	v_exp_f32_e32 v3, v3
	v_or_b32_e32 v2, 56, v78
	v_add_f32_e32 v3, 1.0, v3
	v_div_scale_f32 v4, s[4:5], v3, v3, v14
	v_rcp_f32_e32 v5, v4
	s_nop 0
	v_fma_f32 v6, -v4, v5, 1.0
	v_fmac_f32_e32 v5, v6, v5
	v_div_scale_f32 v6, vcc, v14, v3, v14
	v_mul_f32_e32 v7, v6, v5
	v_fma_f32 v8, -v4, v7, v6
	v_fmac_f32_e32 v7, v8, v5
	v_fma_f32 v4, -v4, v7, v6
	v_div_fmas_f32 v4, v4, v5, v7
	v_div_fixup_f32 v3, v4, v3, v14
	v_mul_f32_e32 v3, v30, v3
	v_bfe_u32 v4, v3, 16, 1
	v_add3_u32 v4, v3, v4, s26
	v_mad_i64_i32 v[2:3], s[4:5], v2, s50, v[76:77]
	global_store_short_d16_hi v[2:3], v4, off
	v_mul_f32_e32 v3, 0xbfb8aa3b, v15
	v_exp_f32_e32 v3, v3
	v_or_b32_e32 v2, 57, v78
	v_add_f32_e32 v3, 1.0, v3
	v_div_scale_f32 v4, s[4:5], v3, v3, v15
	v_rcp_f32_e32 v5, v4
	s_nop 0
	v_fma_f32 v6, -v4, v5, 1.0
	v_fmac_f32_e32 v5, v6, v5
	v_div_scale_f32 v6, vcc, v15, v3, v15
	v_mul_f32_e32 v7, v6, v5
	v_fma_f32 v8, -v4, v7, v6
	v_fmac_f32_e32 v7, v8, v5
	v_fma_f32 v4, -v4, v7, v6
	v_div_fmas_f32 v4, v4, v5, v7
	v_div_fixup_f32 v3, v4, v3, v15
	v_mul_f32_e32 v3, v31, v3
	v_bfe_u32 v4, v3, 16, 1
	v_add3_u32 v4, v3, v4, s26
	v_mad_i64_i32 v[2:3], s[4:5], v2, s50, v[76:77]
	global_store_short_d16_hi v[2:3], v4, off
	v_mul_f32_e32 v3, 0xbfb8aa3b, v16
	v_exp_f32_e32 v3, v3
	v_or_b32_e32 v2, 58, v78
	v_add_f32_e32 v3, 1.0, v3
	v_div_scale_f32 v4, s[4:5], v3, v3, v16
	v_rcp_f32_e32 v5, v4
	s_nop 0
	v_fma_f32 v6, -v4, v5, 1.0
	v_fmac_f32_e32 v5, v6, v5
	v_div_scale_f32 v6, vcc, v16, v3, v16
	v_mul_f32_e32 v7, v6, v5
	v_fma_f32 v8, -v4, v7, v6
	v_fmac_f32_e32 v7, v8, v5
	v_fma_f32 v4, -v4, v7, v6
	v_div_fmas_f32 v4, v4, v5, v7
	v_div_fixup_f32 v3, v4, v3, v16
	v_mul_f32_e32 v3, v32, v3
	v_bfe_u32 v4, v3, 16, 1
	v_add3_u32 v4, v3, v4, s26
	v_mad_i64_i32 v[2:3], s[4:5], v2, s50, v[76:77]
	global_store_short_d16_hi v[2:3], v4, off
	v_mul_f32_e32 v3, 0xbfb8aa3b, v17
	v_exp_f32_e32 v3, v3
	v_or_b32_e32 v2, 59, v78
	v_add_f32_e32 v3, 1.0, v3
	v_div_scale_f32 v4, s[4:5], v3, v3, v17
	v_rcp_f32_e32 v5, v4
	s_nop 0
	v_fma_f32 v6, -v4, v5, 1.0
	v_fmac_f32_e32 v5, v6, v5
	v_div_scale_f32 v6, vcc, v17, v3, v17
	v_mul_f32_e32 v7, v6, v5
	v_fma_f32 v8, -v4, v7, v6
	v_fmac_f32_e32 v7, v8, v5
	v_fma_f32 v4, -v4, v7, v6
	v_div_fmas_f32 v4, v4, v5, v7
	v_div_fixup_f32 v3, v4, v3, v17
	v_mul_f32_e32 v3, v33, v3
	v_bfe_u32 v4, v3, 16, 1
	v_add3_u32 v4, v3, v4, s26
	v_mad_i64_i32 v[2:3], s[4:5], v2, s50, v[76:77]
	global_store_short_d16_hi v[2:3], v4, off
	v_readlane_b32 s5, v255, 48
	s_cmp_eq_u32 s5, 0
	s_cbranch_scc0 .Lg1_pair_done
	s_mov_b32 s5, 1
	s_nop 0
	v_writelane_b32 v255, s5, 48
	v_mov_b32_e32 v34, v132
	v_mov_b32_e32 v35, v133
	v_mov_b32_e32 v36, v134
	v_mov_b32_e32 v37, v135
	v_mov_b32_e32 v38, v136
	v_mov_b32_e32 v39, v137
	v_mov_b32_e32 v40, v138
	v_mov_b32_e32 v41, v139
	v_mov_b32_e32 v42, v140
	v_mov_b32_e32 v43, v141
	v_mov_b32_e32 v44, v142
	v_mov_b32_e32 v45, v143
	v_mov_b32_e32 v46, v144
	v_mov_b32_e32 v47, v145
	v_mov_b32_e32 v48, v146
	v_mov_b32_e32 v49, v147
	v_mov_b32_e32 v50, v148
	v_mov_b32_e32 v51, v149
	v_mov_b32_e32 v52, v150
	v_mov_b32_e32 v53, v151
	v_mov_b32_e32 v54, v152
	v_mov_b32_e32 v55, v153
	v_mov_b32_e32 v56, v154
	v_mov_b32_e32 v57, v155
	v_mov_b32_e32 v58, v156
	v_mov_b32_e32 v59, v157
	v_mov_b32_e32 v60, v158
	v_mov_b32_e32 v61, v159
	v_mov_b32_e32 v62, v160
	v_mov_b32_e32 v63, v161
	v_mov_b32_e32 v64, v162
	v_mov_b32_e32 v65, v163
	v_mov_b32_e32 v2, v164
	v_mov_b32_e32 v3, v165
	v_mov_b32_e32 v4, v166
	v_mov_b32_e32 v5, v167
	v_mov_b32_e32 v6, v168
	v_mov_b32_e32 v7, v169
	v_mov_b32_e32 v8, v170
	v_mov_b32_e32 v9, v171
	v_mov_b32_e32 v10, v172
	v_mov_b32_e32 v11, v173
	v_mov_b32_e32 v12, v174
	v_mov_b32_e32 v13, v175
	v_mov_b32_e32 v14, v176
	v_mov_b32_e32 v15, v177
	v_mov_b32_e32 v16, v178
	v_mov_b32_e32 v17, v179
	v_mov_b32_e32 v18, v180
	v_mov_b32_e32 v19, v181
	v_mov_b32_e32 v20, v182
	v_mov_b32_e32 v21, v183
	v_mov_b32_e32 v22, v184
	v_mov_b32_e32 v23, v185
	v_mov_b32_e32 v24, v186
	v_mov_b32_e32 v25, v187
	v_mov_b32_e32 v26, v188
	v_mov_b32_e32 v27, v189
	v_mov_b32_e32 v28, v190
	v_mov_b32_e32 v29, v191
	v_mov_b32_e32 v30, v192
	v_mov_b32_e32 v31, v193
	v_mov_b32_e32 v32, v194
	v_mov_b32_e32 v33, v195
	s_and_b32 s4, s0, 0xffffffc0
	s_add_u32 s4, s4, 64
	s_lshl_b32 s1, s0, 7
	s_and_b32 s1, s1, 0x1f80
	s_branch .Lg1_epi
.Lg1_pair_done:
	s_mov_b32 s5, 0
	s_nop 0
	v_writelane_b32 v255, s5, 48
	v_readlane_b32 s0, v255, 47
	s_load_dword s1, s[48:49], 0x0
	s_waitcnt lgkmcnt(0)
	s_add_i32 s0, s1, s0
	s_cmpk_gt_i32 s0, 0x57f
	s_cbranch_scc1 .Lg1_exit
	v_writelane_b32 v255, s0, 47
	s_lshr_b32 s1, s0, 6
	s_lshl_b32 s1, s1, 7
	s_and_b32 s0, s0, 63
	s_or_b32 s0, s0, s1
	s_branch .LBB0_77
.Lg1_exit:
	v_mov_b32_e32 v110, 0x12ff0
	ds_write_b32 v110, v196
	ds_write_b32 v110, v205 offset:4
	s_waitcnt lgkmcnt(0)

	.amdhsa_kernel _Z4mega6Paramsii
		.amdhsa_group_segment_fixed_size 4096
		.amdhsa_private_segment_fixed_size 0
		.amdhsa_kernarg_size 472
		.amdhsa_user_sgpr_count 2
		.amdhsa_user_sgpr_dispatch_ptr 0
		.amdhsa_user_sgpr_queue_ptr 0
		.amdhsa_user_sgpr_kernarg_segment_ptr 1
		.amdhsa_user_sgpr_dispatch_id 0
		.amdhsa_user_sgpr_kernarg_preload_length 0
		.amdhsa_user_sgpr_kernarg_preload_offset 0
		.amdhsa_user_sgpr_private_segment_size 0
		.amdhsa_uses_dynamic_stack 0
		.amdhsa_enable_private_segment 0
		.amdhsa_system_sgpr_workgroup_id_x 1
		.amdhsa_system_sgpr_workgroup_id_y 0
		.amdhsa_system_sgpr_workgroup_id_z 0
		.amdhsa_system_sgpr_workgroup_info 0
		.amdhsa_system_vgpr_workitem_id 0
		.amdhsa_next_free_vgpr 256
		.amdhsa_next_free_sgpr 102
		.amdhsa_accum_offset 256
		.amdhsa_reserve_vcc 1
		.amdhsa_float_round_mode_32 0
		.amdhsa_float_round_mode_16_64 0
		.amdhsa_float_denorm_mode_32 3
		.amdhsa_float_denorm_mode_16_64 3
		.amdhsa_dx10_clamp 1
		.amdhsa_ieee_mode 1
		.amdhsa_fp16_overflow 0
		.amdhsa_tg_split 0
		.amdhsa_exception_fp_ieee_invalid_op 0
		.amdhsa_exception_fp_denorm_src 0
		.amdhsa_exception_fp_ieee_div_zero 0
		.amdhsa_exception_fp_ieee_overflow 0
		.amdhsa_exception_fp_ieee_underflow 0
		.amdhsa_exception_fp_ieee_inexact 0
		.amdhsa_exception_int_div_zero 0
	.end_amdhsa_kernel

amdhsa.kernels:
  - .agpr_count:     0
    .args:
      - .offset:         0
        .size:           208
        .value_kind:     by_value
      - .offset:         208
        .size:           4
        .value_kind:     by_value
      - .offset:         212
        .size:           4
        .value_kind:     by_value
      - .offset:         216
        .size:           4
        .value_kind:     hidden_block_count_x
      - .offset:         220
        .size:           4
        .value_kind:     hidden_block_count_y
      - .offset:         224
        .size:           4
        .value_kind:     hidden_block_count_z
      - .offset:         228
        .size:           2
        .value_kind:     hidden_group_size_x
      - .offset:         230
        .size:           2
        .value_kind:     hidden_group_size_y
      - .offset:         232
        .size:           2
        .value_kind:     hidden_group_size_z
      - .offset:         234
        .size:           2
        .value_kind:     hidden_remainder_x
      - .offset:         236
        .size:           2
        .value_kind:     hidden_remainder_y
      - .offset:         238
        .size:           2
        .value_kind:     hidden_remainder_z
      - .offset:         256
        .size:           8
        .value_kind:     hidden_global_offset_x
      - .offset:         264
        .size:           8
        .value_kind:     hidden_global_offset_y
      - .offset:         272
        .size:           8
        .value_kind:     hidden_global_offset_z
      - .offset:         280
        .size:           2
        .value_kind:     hidden_grid_dims
      - .offset:         336
        .size:           4
        .value_kind:     hidden_dynamic_lds_size
    .group_segment_fixed_size: 4096
    .kernarg_segment_align: 8
    .kernarg_segment_size: 472
    .language:       OpenCL C
    .language_version:
      - 2
      - 0
    .max_flat_workgroup_size: 256
    .name:           _Z4mega6Paramsii
    .private_segment_fixed_size: 0
    .sgpr_count:     108
    .sgpr_spill_count: 237
    .symbol:         _Z4mega6Paramsii.kd
    .uniform_work_group_size: 1
    .uses_dynamic_stack: false
    .vgpr_count:     256
    .vgpr_spill_count: 0
    .wavefront_size: 64
